# code placement: s_nop pads so every GEMM K-loop MFMA block starts at byte phase 0 mod 8 (20 of 32 were at phase 4)
# speedup vs baseline: 1.0093x; 1.0078x over previous
.LBB0_217:
	s_add_u32 s36, s34, 0xfffc0080
	s_addc_u32 s37, s35, -1
	s_cmp_eq_u32 s71, 12
	s_cselect_b32 s39, s7, s37
	s_cselect_b32 s38, s25, s36
	s_cselect_b32 s37, s23, s70
	s_cselect_b32 s36, s68, s69
	v_lshl_add_u64 v[150:151], s[34:35], 0, v[138:139]
	s_add_i32 m0, s31, 0xc000
	s_nop 0
	global_load_lds_dwordx4 v[150:151], off
	v_lshl_add_u64 v[150:151], s[34:35], 0, v[140:141]
	s_add_i32 m0, s31, 0xe000
	s_nop 0
	global_load_lds_dwordx4 v[150:151], off
	ds_read_b128 v[146:149], v155
	ds_read_b128 v[158:161], v155 offset:1024
	ds_read_b128 v[162:165], v155 offset:2048
	ds_read_b128 v[166:169], v155 offset:3072
	ds_read_b128 v[170:173], v156
	ds_read_b128 v[174:177], v156 offset:1024
	ds_read_b128 v[178:181], v156 offset:2048
	ds_read_b128 v[182:185], v156 offset:3072
	ds_read_b128 v[186:189], v157
	ds_read_b128 v[190:193], v157 offset:1024
	ds_read_b128 v[194:197], v157 offset:2048
	ds_read_b128 v[198:201], v157 offset:3072
	ds_read_b128 v[202:205], v157 offset:4096
	ds_read_b128 v[206:209], v157 offset:5120
	ds_read_b128 v[210:213], v157 offset:6144
	ds_read_b128 v[214:217], v157 offset:7168
	s_waitcnt vmcnt(8)
	s_waitcnt lgkmcnt(0)
	s_setprio 1
	s_barrier
	v_mfma_f32_16x16x32_bf16 v[124:127], v[146:149], v[186:189], v[124:127]
	v_mfma_f32_16x16x32_bf16 v[120:123], v[162:165], v[186:189], v[120:123]
	v_mfma_f32_16x16x32_bf16 v[108:111], v[146:149], v[194:197], v[108:111]
	v_mfma_f32_16x16x32_bf16 v[104:107], v[162:165], v[194:197], v[104:107]
	v_mfma_f32_16x16x32_bf16 v[92:95], v[146:149], v[202:205], v[92:95]
	v_mfma_f32_16x16x32_bf16 v[88:91], v[162:165], v[202:205], v[88:91]
	v_mfma_f32_16x16x32_bf16 v[76:79], v[146:149], v[210:213], v[76:79]
	v_mfma_f32_16x16x32_bf16 v[72:75], v[162:165], v[210:213], v[72:75]
	v_mfma_f32_16x16x32_bf16 v[124:127], v[158:161], v[190:193], v[124:127]
	v_mfma_f32_16x16x32_bf16 v[120:123], v[166:169], v[190:193], v[120:123]
	v_mfma_f32_16x16x32_bf16 v[108:111], v[158:161], v[198:201], v[108:111]
	v_mfma_f32_16x16x32_bf16 v[104:107], v[166:169], v[198:201], v[104:107]
	v_mfma_f32_16x16x32_bf16 v[92:95], v[158:161], v[206:209], v[92:95]
	v_mfma_f32_16x16x32_bf16 v[88:91], v[166:169], v[206:209], v[88:91]
	v_mfma_f32_16x16x32_bf16 v[76:79], v[158:161], v[214:217], v[76:79]
	v_mfma_f32_16x16x32_bf16 v[72:75], v[166:169], v[214:217], v[72:75]
	s_setprio 0
	s_setprio 1
	v_mfma_f32_16x16x32_bf16 v[116:119], v[170:173], v[186:189], v[116:119]
	v_mfma_f32_16x16x32_bf16 v[112:115], v[178:181], v[186:189], v[112:115]
	v_mfma_f32_16x16x32_bf16 v[100:103], v[170:173], v[194:197], v[100:103]
	v_mfma_f32_16x16x32_bf16 v[96:99], v[178:181], v[194:197], v[96:99]
	v_mfma_f32_16x16x32_bf16 v[84:87], v[170:173], v[202:205], v[84:87]
	v_mfma_f32_16x16x32_bf16 v[80:83], v[178:181], v[202:205], v[80:83]
	v_mfma_f32_16x16x32_bf16 v[68:71], v[170:173], v[210:213], v[68:71]
	v_mfma_f32_16x16x32_bf16 v[64:67], v[178:181], v[210:213], v[64:67]
	v_mfma_f32_16x16x32_bf16 v[116:119], v[174:177], v[190:193], v[116:119]
	v_mfma_f32_16x16x32_bf16 v[112:115], v[182:185], v[190:193], v[112:115]
	v_mfma_f32_16x16x32_bf16 v[100:103], v[174:177], v[198:201], v[100:103]
	v_mfma_f32_16x16x32_bf16 v[96:99], v[182:185], v[198:201], v[96:99]
	v_mfma_f32_16x16x32_bf16 v[84:87], v[174:177], v[206:209], v[84:87]
	v_mfma_f32_16x16x32_bf16 v[80:83], v[182:185], v[206:209], v[80:83]
	v_mfma_f32_16x16x32_bf16 v[68:71], v[174:177], v[214:217], v[68:71]
	v_mfma_f32_16x16x32_bf16 v[64:67], v[182:185], v[214:217], v[64:67]
	s_barrier
	s_setprio 0
	s_add_i32 s72, s65, s43
	v_lshl_add_u64 v[150:151], s[36:37], 0, v[130:131]
	s_mov_b32 m0, s72
	s_nop 0
	global_load_lds_dwordx4 v[150:151], off
	s_add_i32 m0, s72, 0x2000
	s_add_u32 s72, s36, 0x40000
	v_lshl_add_u64 v[218:219], s[36:37], 0, v[134:135]
	s_addc_u32 s73, s37, 0
	s_add_i32 s74, s67, s43
	global_load_lds_dwordx4 v[218:219], off
	v_lshl_add_u64 v[220:221], s[72:73], 0, v[130:131]
	s_mov_b32 m0, s74
	v_lshl_add_u64 v[222:223], s[38:39], 0, v[132:133]
	global_load_lds_dwordx4 v[220:221], off
	v_lshl_add_u64 v[220:221], s[72:73], 0, v[134:135]
	s_add_i32 m0, s74, 0x2000
	s_nop 0
	global_load_lds_dwordx4 v[220:221], off
	v_lshl_add_u64 v[220:221], s[38:39], 0, v[128:129]
	s_mov_b32 m0, s31
	s_nop 0
	global_load_lds_dwordx4 v[220:221], off
	s_mov_b32 m0, s46
	s_nop 0
	global_load_lds_dwordx4 v[222:223], off
	ds_read_b128 v[186:189], v157 offset:16384
	ds_read_b128 v[190:193], v157 offset:17408
	ds_read_b128 v[194:197], v157 offset:18432
	ds_read_b128 v[198:201], v157 offset:19456
	ds_read_b128 v[202:205], v157 offset:20480
	ds_read_b128 v[206:209], v157 offset:21504
	ds_read_b128 v[210:213], v157 offset:22528
	ds_read_b128 v[214:217], v157 offset:23552
	s_nop 0
	s_waitcnt vmcnt(8)
	s_waitcnt lgkmcnt(0)
	s_setprio 1
	s_barrier
	v_mfma_f32_16x16x32_bf16 v[60:63], v[146:149], v[186:189], v[60:63]
	v_mfma_f32_16x16x32_bf16 v[56:59], v[162:165], v[186:189], v[56:59]
	v_mfma_f32_16x16x32_bf16 v[44:47], v[146:149], v[194:197], v[44:47]
	v_mfma_f32_16x16x32_bf16 v[40:43], v[162:165], v[194:197], v[40:43]
	v_mfma_f32_16x16x32_bf16 v[28:31], v[146:149], v[202:205], v[28:31]
	v_mfma_f32_16x16x32_bf16 v[24:27], v[162:165], v[202:205], v[24:27]
	v_mfma_f32_16x16x32_bf16 v[12:15], v[146:149], v[210:213], v[12:15]
	v_mfma_f32_16x16x32_bf16 v[8:11], v[162:165], v[210:213], v[8:11]
	v_mfma_f32_16x16x32_bf16 v[60:63], v[158:161], v[190:193], v[60:63]
	v_mfma_f32_16x16x32_bf16 v[56:59], v[166:169], v[190:193], v[56:59]
	v_mfma_f32_16x16x32_bf16 v[44:47], v[158:161], v[198:201], v[44:47]
	v_mfma_f32_16x16x32_bf16 v[40:43], v[166:169], v[198:201], v[40:43]
	v_mfma_f32_16x16x32_bf16 v[28:31], v[158:161], v[206:209], v[28:31]
	v_mfma_f32_16x16x32_bf16 v[24:27], v[166:169], v[206:209], v[24:27]
	v_mfma_f32_16x16x32_bf16 v[12:15], v[158:161], v[214:217], v[12:15]
	v_mfma_f32_16x16x32_bf16 v[8:11], v[166:169], v[214:217], v[8:11]
	s_setprio 0
	s_setprio 1
	v_mfma_f32_16x16x32_bf16 v[52:55], v[170:173], v[186:189], v[52:55]
	v_mfma_f32_16x16x32_bf16 v[48:51], v[178:181], v[186:189], v[48:51]
	v_mfma_f32_16x16x32_bf16 v[36:39], v[170:173], v[194:197], v[36:39]
	v_mfma_f32_16x16x32_bf16 v[32:35], v[178:181], v[194:197], v[32:35]
	v_mfma_f32_16x16x32_bf16 v[20:23], v[170:173], v[202:205], v[20:23]
	v_mfma_f32_16x16x32_bf16 v[16:19], v[178:181], v[202:205], v[16:19]
	v_mfma_f32_16x16x32_bf16 v[4:7], v[170:173], v[210:213], v[4:7]
	v_mfma_f32_16x16x32_bf16 v[0:3], v[178:181], v[210:213], v[0:3]
	v_mfma_f32_16x16x32_bf16 v[52:55], v[174:177], v[190:193], v[52:55]
	v_mfma_f32_16x16x32_bf16 v[48:51], v[182:185], v[190:193], v[48:51]
	v_mfma_f32_16x16x32_bf16 v[36:39], v[174:177], v[198:201], v[36:39]
	v_mfma_f32_16x16x32_bf16 v[32:35], v[182:185], v[198:201], v[32:35]
	v_mfma_f32_16x16x32_bf16 v[20:23], v[174:177], v[206:209], v[20:23]
	v_mfma_f32_16x16x32_bf16 v[16:19], v[182:185], v[206:209], v[16:19]
	v_mfma_f32_16x16x32_bf16 v[4:7], v[174:177], v[214:217], v[4:7]
	v_mfma_f32_16x16x32_bf16 v[0:3], v[182:185], v[214:217], v[0:3]
	s_barrier
	s_setprio 0
	s_add_i32 s72, 0, 0x18000
	s_add_i32 s73, 0, 0x1c000
	s_add_u32 s38, s38, 0x40000
	s_addc_u32 s39, s39, 0
	s_mov_b32 m0, s47
	v_lshl_add_u64 v[224:225], s[38:39], 0, v[128:129]
	global_load_lds_dwordx4 v[224:225], off
	v_lshl_add_u64 v[224:225], s[38:39], 0, v[132:133]
	s_mov_b32 m0, s48
	s_nop 0
	global_load_lds_dwordx4 v[224:225], off
	v_add_u32_e32 v136, s72, v153
	ds_read_b128 v[146:149], v136
	ds_read_b128 v[158:161], v136 offset:1024
	ds_read_b128 v[162:165], v136 offset:2048
	ds_read_b128 v[166:169], v136 offset:3072
	v_add_u32_e32 v136, s73, v153
	ds_read_b128 v[170:173], v136
	ds_read_b128 v[174:177], v136 offset:1024
	ds_read_b128 v[178:181], v136 offset:2048
	ds_read_b128 v[182:185], v136 offset:3072
	ds_read_b128 v[186:189], v157 offset:32768
	ds_read_b128 v[190:193], v157 offset:33792
	ds_read_b128 v[194:197], v157 offset:34816
	ds_read_b128 v[198:201], v157 offset:35840
	ds_read_b128 v[202:205], v157 offset:36864
	ds_read_b128 v[206:209], v157 offset:37888
	ds_read_b128 v[210:213], v157 offset:38912
	ds_read_b128 v[214:217], v157 offset:39936
	s_waitcnt vmcnt(8)
	s_waitcnt lgkmcnt(0)
	s_setprio 1
	s_barrier
	v_mfma_f32_16x16x32_bf16 v[124:127], v[146:149], v[186:189], v[124:127]
	v_mfma_f32_16x16x32_bf16 v[120:123], v[162:165], v[186:189], v[120:123]
	v_mfma_f32_16x16x32_bf16 v[108:111], v[146:149], v[194:197], v[108:111]
	v_mfma_f32_16x16x32_bf16 v[104:107], v[162:165], v[194:197], v[104:107]
	v_mfma_f32_16x16x32_bf16 v[92:95], v[146:149], v[202:205], v[92:95]
	v_mfma_f32_16x16x32_bf16 v[88:91], v[162:165], v[202:205], v[88:91]
	v_mfma_f32_16x16x32_bf16 v[76:79], v[146:149], v[210:213], v[76:79]
	v_mfma_f32_16x16x32_bf16 v[72:75], v[162:165], v[210:213], v[72:75]
	v_mfma_f32_16x16x32_bf16 v[124:127], v[158:161], v[190:193], v[124:127]
	v_mfma_f32_16x16x32_bf16 v[120:123], v[166:169], v[190:193], v[120:123]
	v_mfma_f32_16x16x32_bf16 v[108:111], v[158:161], v[198:201], v[108:111]
	v_mfma_f32_16x16x32_bf16 v[104:107], v[166:169], v[198:201], v[104:107]
	v_mfma_f32_16x16x32_bf16 v[92:95], v[158:161], v[206:209], v[92:95]
	v_mfma_f32_16x16x32_bf16 v[88:91], v[166:169], v[206:209], v[88:91]
	v_mfma_f32_16x16x32_bf16 v[76:79], v[158:161], v[214:217], v[76:79]
	v_mfma_f32_16x16x32_bf16 v[72:75], v[166:169], v[214:217], v[72:75]
	s_setprio 0
	s_setprio 1
	v_mfma_f32_16x16x32_bf16 v[116:119], v[170:173], v[186:189], v[116:119]
	v_mfma_f32_16x16x32_bf16 v[112:115], v[178:181], v[186:189], v[112:115]
	v_mfma_f32_16x16x32_bf16 v[100:103], v[170:173], v[194:197], v[100:103]
	v_mfma_f32_16x16x32_bf16 v[96:99], v[178:181], v[194:197], v[96:99]
	v_mfma_f32_16x16x32_bf16 v[84:87], v[170:173], v[202:205], v[84:87]
	v_mfma_f32_16x16x32_bf16 v[80:83], v[178:181], v[202:205], v[80:83]
	v_mfma_f32_16x16x32_bf16 v[68:71], v[170:173], v[210:213], v[68:71]
	v_mfma_f32_16x16x32_bf16 v[64:67], v[178:181], v[210:213], v[64:67]
	v_mfma_f32_16x16x32_bf16 v[116:119], v[174:177], v[190:193], v[116:119]
	v_mfma_f32_16x16x32_bf16 v[112:115], v[182:185], v[190:193], v[112:115]
	v_mfma_f32_16x16x32_bf16 v[100:103], v[174:177], v[198:201], v[100:103]
	v_mfma_f32_16x16x32_bf16 v[96:99], v[182:185], v[198:201], v[96:99]
	v_mfma_f32_16x16x32_bf16 v[84:87], v[174:177], v[206:209], v[84:87]
	v_mfma_f32_16x16x32_bf16 v[80:83], v[182:185], v[206:209], v[80:83]
	v_mfma_f32_16x16x32_bf16 v[68:71], v[174:177], v[214:217], v[68:71]
	v_mfma_f32_16x16x32_bf16 v[64:67], v[182:185], v[214:217], v[64:67]
	s_barrier
	s_setprio 0
	s_add_i32 s38, s72, s43
	v_lshl_add_u64 v[150:151], v[150:151], 0, s[12:13]
	s_mov_b32 m0, s38
	s_nop 0
	global_load_lds_dwordx4 v[150:151], off
	s_add_i32 m0, s38, 0x2000
	s_add_u32 s36, s36, 0x40080
	v_lshl_add_u64 v[150:151], v[218:219], 0, s[12:13]
	s_addc_u32 s37, s37, 0
	s_add_i32 s38, s73, s43
	global_load_lds_dwordx4 v[150:151], off
	v_lshl_add_u64 v[150:151], s[36:37], 0, v[130:131]
	s_mov_b32 m0, s38
	s_nop 0
	global_load_lds_dwordx4 v[150:151], off
	v_lshl_add_u64 v[150:151], s[36:37], 0, v[134:135]
	s_add_i32 m0, s38, 0x2000
	s_nop 0
	global_load_lds_dwordx4 v[150:151], off
	v_lshl_add_u64 v[150:151], v[220:221], 0, s[12:13]
	s_mov_b32 m0, s60
	s_nop 0
	global_load_lds_dwordx4 v[150:151], off
	v_lshl_add_u64 v[150:151], v[222:223], 0, s[12:13]
	s_mov_b32 m0, s61
	s_nop 0
	global_load_lds_dwordx4 v[150:151], off
	ds_read_b128 v[186:189], v157 offset:49152
	ds_read_b128 v[190:193], v157 offset:50176
	ds_read_b128 v[194:197], v157 offset:51200
	ds_read_b128 v[198:201], v157 offset:52224
	ds_read_b128 v[202:205], v157 offset:53248
	ds_read_b128 v[206:209], v157 offset:54272
	ds_read_b128 v[210:213], v157 offset:55296
	ds_read_b128 v[214:217], v157 offset:56320
	s_waitcnt vmcnt(8)
	s_waitcnt lgkmcnt(0)
	s_setprio 1
	s_barrier
	v_mfma_f32_16x16x32_bf16 v[60:63], v[146:149], v[186:189], v[60:63]
	v_mfma_f32_16x16x32_bf16 v[56:59], v[162:165], v[186:189], v[56:59]
	v_mfma_f32_16x16x32_bf16 v[44:47], v[146:149], v[194:197], v[44:47]
	v_mfma_f32_16x16x32_bf16 v[40:43], v[162:165], v[194:197], v[40:43]
	v_mfma_f32_16x16x32_bf16 v[28:31], v[146:149], v[202:205], v[28:31]
	v_mfma_f32_16x16x32_bf16 v[24:27], v[162:165], v[202:205], v[24:27]
	v_mfma_f32_16x16x32_bf16 v[12:15], v[146:149], v[210:213], v[12:15]
	v_mfma_f32_16x16x32_bf16 v[8:11], v[162:165], v[210:213], v[8:11]
	v_mfma_f32_16x16x32_bf16 v[60:63], v[158:161], v[190:193], v[60:63]
	v_mfma_f32_16x16x32_bf16 v[56:59], v[166:169], v[190:193], v[56:59]
	v_mfma_f32_16x16x32_bf16 v[44:47], v[158:161], v[198:201], v[44:47]
	v_mfma_f32_16x16x32_bf16 v[40:43], v[166:169], v[198:201], v[40:43]
	v_mfma_f32_16x16x32_bf16 v[28:31], v[158:161], v[206:209], v[28:31]
	v_mfma_f32_16x16x32_bf16 v[24:27], v[166:169], v[206:209], v[24:27]
	v_mfma_f32_16x16x32_bf16 v[12:15], v[158:161], v[214:217], v[12:15]
	v_mfma_f32_16x16x32_bf16 v[8:11], v[166:169], v[214:217], v[8:11]
	s_setprio 0
	s_setprio 1
	v_mfma_f32_16x16x32_bf16 v[52:55], v[170:173], v[186:189], v[52:55]
	v_mfma_f32_16x16x32_bf16 v[48:51], v[178:181], v[186:189], v[48:51]
	v_mfma_f32_16x16x32_bf16 v[36:39], v[170:173], v[194:197], v[36:39]
	v_mfma_f32_16x16x32_bf16 v[32:35], v[178:181], v[194:197], v[32:35]
	v_mfma_f32_16x16x32_bf16 v[20:23], v[170:173], v[202:205], v[20:23]
	v_mfma_f32_16x16x32_bf16 v[16:19], v[178:181], v[202:205], v[16:19]
	v_mfma_f32_16x16x32_bf16 v[4:7], v[170:173], v[210:213], v[4:7]
	v_mfma_f32_16x16x32_bf16 v[0:3], v[178:181], v[210:213], v[0:3]
	v_mfma_f32_16x16x32_bf16 v[52:55], v[174:177], v[190:193], v[52:55]
	v_mfma_f32_16x16x32_bf16 v[48:51], v[182:185], v[190:193], v[48:51]
	v_mfma_f32_16x16x32_bf16 v[36:39], v[174:177], v[198:201], v[36:39]
	v_mfma_f32_16x16x32_bf16 v[32:35], v[182:185], v[198:201], v[32:35]
	v_mfma_f32_16x16x32_bf16 v[20:23], v[174:177], v[206:209], v[20:23]
	v_mfma_f32_16x16x32_bf16 v[16:19], v[182:185], v[206:209], v[16:19]
	v_mfma_f32_16x16x32_bf16 v[4:7], v[174:177], v[214:217], v[4:7]
	v_mfma_f32_16x16x32_bf16 v[0:3], v[182:185], v[214:217], v[0:3]
	s_barrier
	s_setprio 0
	s_add_i32 s71, s71, 2
	s_add_u32 s34, s34, 0x100
	s_addc_u32 s35, s35, 0
	s_add_u32 s69, s69, 0x100
	s_addc_u32 s70, s70, 0
	s_cmp_gt_u32 s71, 13
	s_cbranch_scc0 .LBB0_217
	s_and_b64 vcc, exec, s[14:15]
	s_cbranch_vccz .LBB0_220
	s_barrier

.LBB0_471:
	s_add_u32 s34, s30, 0xfffc0080
	s_addc_u32 s35, s31, -1
	s_cmp_eq_u32 s69, 12
	s_cselect_b32 s37, s21, s35
	s_cselect_b32 s36, s27, s34
	s_cselect_b32 s35, s19, s68
	s_cselect_b32 s34, s64, s65
	v_lshl_add_u64 v[214:215], s[30:31], 0, v[184:185]
	s_add_i32 m0, s29, 0xc000
	s_nop 0
	global_load_lds_dwordx4 v[214:215], off
	v_lshl_add_u64 v[214:215], s[30:31], 0, v[186:187]
	s_add_i32 m0, s29, 0xe000
	s_nop 0
	global_load_lds_dwordx4 v[214:215], off
	ds_read_b128 v[128:131], v207
	ds_read_b128 v[132:135], v207 offset:1024
	ds_read_b128 v[136:139], v207 offset:2048
	ds_read_b128 v[140:143], v207 offset:3072
	ds_read_b128 v[144:147], v208
	ds_read_b128 v[148:151], v208 offset:1024
	ds_read_b128 v[152:155], v208 offset:2048
	ds_read_b128 v[156:159], v208 offset:3072
	ds_read_b128 v[160:163], v209
	ds_read_b128 v[164:167], v209 offset:1024
	ds_read_b128 v[168:171], v209 offset:2048
	ds_read_b128 v[172:175], v209 offset:3072
	ds_read_b128 v[192:195], v209 offset:4096
	ds_read_b128 v[196:199], v209 offset:5120
	ds_read_b128 v[200:203], v209 offset:6144
	ds_read_b128 v[210:213], v209 offset:7168
	s_nop 0
	s_waitcnt vmcnt(8)
	s_waitcnt lgkmcnt(0)
	s_setprio 1
	s_barrier
	v_mfma_f32_16x16x32_bf16 v[124:127], v[128:131], v[160:163], v[124:127]
	v_mfma_f32_16x16x32_bf16 v[120:123], v[136:139], v[160:163], v[120:123]
	v_mfma_f32_16x16x32_bf16 v[108:111], v[128:131], v[168:171], v[108:111]
	v_mfma_f32_16x16x32_bf16 v[104:107], v[136:139], v[168:171], v[104:107]
	v_mfma_f32_16x16x32_bf16 v[92:95], v[128:131], v[192:195], v[92:95]
	v_mfma_f32_16x16x32_bf16 v[88:91], v[136:139], v[192:195], v[88:91]
	v_mfma_f32_16x16x32_bf16 v[76:79], v[128:131], v[200:203], v[76:79]
	v_mfma_f32_16x16x32_bf16 v[72:75], v[136:139], v[200:203], v[72:75]
	v_mfma_f32_16x16x32_bf16 v[124:127], v[132:135], v[164:167], v[124:127]
	v_mfma_f32_16x16x32_bf16 v[120:123], v[140:143], v[164:167], v[120:123]
	v_mfma_f32_16x16x32_bf16 v[108:111], v[132:135], v[172:175], v[108:111]
	v_mfma_f32_16x16x32_bf16 v[104:107], v[140:143], v[172:175], v[104:107]
	v_mfma_f32_16x16x32_bf16 v[92:95], v[132:135], v[196:199], v[92:95]
	v_mfma_f32_16x16x32_bf16 v[88:91], v[140:143], v[196:199], v[88:91]
	v_mfma_f32_16x16x32_bf16 v[76:79], v[132:135], v[210:213], v[76:79]
	v_mfma_f32_16x16x32_bf16 v[72:75], v[140:143], v[210:213], v[72:75]
	s_setprio 0
	s_setprio 1
	v_mfma_f32_16x16x32_bf16 v[116:119], v[144:147], v[160:163], v[116:119]
	v_mfma_f32_16x16x32_bf16 v[112:115], v[152:155], v[160:163], v[112:115]
	v_mfma_f32_16x16x32_bf16 v[100:103], v[144:147], v[168:171], v[100:103]
	v_mfma_f32_16x16x32_bf16 v[96:99], v[152:155], v[168:171], v[96:99]
	v_mfma_f32_16x16x32_bf16 v[84:87], v[144:147], v[192:195], v[84:87]
	v_mfma_f32_16x16x32_bf16 v[80:83], v[152:155], v[192:195], v[80:83]
	v_mfma_f32_16x16x32_bf16 v[68:71], v[144:147], v[200:203], v[68:71]
	v_mfma_f32_16x16x32_bf16 v[64:67], v[152:155], v[200:203], v[64:67]
	v_mfma_f32_16x16x32_bf16 v[116:119], v[148:151], v[164:167], v[116:119]
	v_mfma_f32_16x16x32_bf16 v[112:115], v[156:159], v[164:167], v[112:115]
	v_mfma_f32_16x16x32_bf16 v[100:103], v[148:151], v[172:175], v[100:103]
	v_mfma_f32_16x16x32_bf16 v[96:99], v[156:159], v[172:175], v[96:99]
	v_mfma_f32_16x16x32_bf16 v[84:87], v[148:151], v[196:199], v[84:87]
	v_mfma_f32_16x16x32_bf16 v[80:83], v[156:159], v[196:199], v[80:83]
	v_mfma_f32_16x16x32_bf16 v[68:71], v[148:151], v[210:213], v[68:71]
	v_mfma_f32_16x16x32_bf16 v[64:67], v[156:159], v[210:213], v[64:67]
	s_barrier
	s_setprio 0
	s_add_i32 s70, s62, s40
	v_lshl_add_u64 v[214:215], s[34:35], 0, v[178:179]
	s_mov_b32 m0, s70
	s_nop 0
	global_load_lds_dwordx4 v[214:215], off
	s_add_i32 m0, s70, 0x2000
	s_add_u32 s70, s34, 0x40000
	v_lshl_add_u64 v[216:217], s[34:35], 0, v[182:183]
	s_addc_u32 s71, s35, 0
	s_add_i32 s72, s63, s40
	global_load_lds_dwordx4 v[216:217], off
	v_lshl_add_u64 v[218:219], s[70:71], 0, v[178:179]
	s_mov_b32 m0, s72
	v_lshl_add_u64 v[220:221], s[36:37], 0, v[180:181]
	global_load_lds_dwordx4 v[218:219], off
	v_lshl_add_u64 v[218:219], s[70:71], 0, v[182:183]
	s_add_i32 m0, s72, 0x2000
	s_nop 0
	global_load_lds_dwordx4 v[218:219], off
	v_lshl_add_u64 v[218:219], s[36:37], 0, v[176:177]
	s_mov_b32 m0, s29
	s_nop 0
	global_load_lds_dwordx4 v[218:219], off
	s_mov_b32 m0, s41
	s_nop 0
	global_load_lds_dwordx4 v[220:221], off
	ds_read_b128 v[160:163], v209 offset:16384
	ds_read_b128 v[164:167], v209 offset:17408
	ds_read_b128 v[168:171], v209 offset:18432
	ds_read_b128 v[172:175], v209 offset:19456
	ds_read_b128 v[192:195], v209 offset:20480
	ds_read_b128 v[196:199], v209 offset:21504
	ds_read_b128 v[200:203], v209 offset:22528
	ds_read_b128 v[210:213], v209 offset:23552
	s_nop 0
	s_waitcnt vmcnt(8)
	s_waitcnt lgkmcnt(0)
	s_setprio 1
	s_barrier
	v_mfma_f32_16x16x32_bf16 v[60:63], v[128:131], v[160:163], v[60:63]
	v_mfma_f32_16x16x32_bf16 v[56:59], v[136:139], v[160:163], v[56:59]
	v_mfma_f32_16x16x32_bf16 v[44:47], v[128:131], v[168:171], v[44:47]
	v_mfma_f32_16x16x32_bf16 v[40:43], v[136:139], v[168:171], v[40:43]
	v_mfma_f32_16x16x32_bf16 v[28:31], v[128:131], v[192:195], v[28:31]
	v_mfma_f32_16x16x32_bf16 v[24:27], v[136:139], v[192:195], v[24:27]
	v_mfma_f32_16x16x32_bf16 v[12:15], v[128:131], v[200:203], v[12:15]
	v_mfma_f32_16x16x32_bf16 v[8:11], v[136:139], v[200:203], v[8:11]
	v_mfma_f32_16x16x32_bf16 v[60:63], v[132:135], v[164:167], v[60:63]
	v_mfma_f32_16x16x32_bf16 v[56:59], v[140:143], v[164:167], v[56:59]
	v_mfma_f32_16x16x32_bf16 v[44:47], v[132:135], v[172:175], v[44:47]
	v_mfma_f32_16x16x32_bf16 v[40:43], v[140:143], v[172:175], v[40:43]
	v_mfma_f32_16x16x32_bf16 v[28:31], v[132:135], v[196:199], v[28:31]
	v_mfma_f32_16x16x32_bf16 v[24:27], v[140:143], v[196:199], v[24:27]
	v_mfma_f32_16x16x32_bf16 v[12:15], v[132:135], v[210:213], v[12:15]
	v_mfma_f32_16x16x32_bf16 v[8:11], v[140:143], v[210:213], v[8:11]
	s_setprio 0
	s_setprio 1
	v_mfma_f32_16x16x32_bf16 v[52:55], v[144:147], v[160:163], v[52:55]
	v_mfma_f32_16x16x32_bf16 v[48:51], v[152:155], v[160:163], v[48:51]
	v_mfma_f32_16x16x32_bf16 v[36:39], v[144:147], v[168:171], v[36:39]
	v_mfma_f32_16x16x32_bf16 v[32:35], v[152:155], v[168:171], v[32:35]
	v_mfma_f32_16x16x32_bf16 v[20:23], v[144:147], v[192:195], v[20:23]
	v_mfma_f32_16x16x32_bf16 v[16:19], v[152:155], v[192:195], v[16:19]
	v_mfma_f32_16x16x32_bf16 v[4:7], v[144:147], v[200:203], v[4:7]
	v_mfma_f32_16x16x32_bf16 v[0:3], v[152:155], v[200:203], v[0:3]
	v_mfma_f32_16x16x32_bf16 v[52:55], v[148:151], v[164:167], v[52:55]
	v_mfma_f32_16x16x32_bf16 v[48:51], v[156:159], v[164:167], v[48:51]
	v_mfma_f32_16x16x32_bf16 v[36:39], v[148:151], v[172:175], v[36:39]
	v_mfma_f32_16x16x32_bf16 v[32:35], v[156:159], v[172:175], v[32:35]
	v_mfma_f32_16x16x32_bf16 v[20:23], v[148:151], v[196:199], v[20:23]
	v_mfma_f32_16x16x32_bf16 v[16:19], v[156:159], v[196:199], v[16:19]
	v_mfma_f32_16x16x32_bf16 v[4:7], v[148:151], v[210:213], v[4:7]
	v_mfma_f32_16x16x32_bf16 v[0:3], v[156:159], v[210:213], v[0:3]
	s_barrier
	s_setprio 0
	s_add_i32 s70, 0, 0x18000
	s_add_i32 s71, 0, 0x1c000
	s_add_u32 s36, s36, 0x40000
	s_addc_u32 s37, s37, 0
	s_mov_b32 m0, s42
	v_lshl_add_u64 v[222:223], s[36:37], 0, v[176:177]
	global_load_lds_dwordx4 v[222:223], off
	v_lshl_add_u64 v[222:223], s[36:37], 0, v[180:181]
	s_mov_b32 m0, s43
	s_nop 0
	global_load_lds_dwordx4 v[222:223], off
	v_add_u32_e32 v140, s70, v206
	v_add_u32_e32 v156, s71, v206
	ds_read_b128 v[128:131], v140
	ds_read_b128 v[132:135], v140 offset:1024
	ds_read_b128 v[136:139], v140 offset:2048
	ds_read_b128 v[140:143], v140 offset:3072
	ds_read_b128 v[144:147], v156
	ds_read_b128 v[148:151], v156 offset:1024
	ds_read_b128 v[152:155], v156 offset:2048
	ds_read_b128 v[156:159], v156 offset:3072
	ds_read_b128 v[160:163], v209 offset:32768
	ds_read_b128 v[164:167], v209 offset:33792
	ds_read_b128 v[168:171], v209 offset:34816
	ds_read_b128 v[172:175], v209 offset:35840
	ds_read_b128 v[192:195], v209 offset:36864
	ds_read_b128 v[196:199], v209 offset:37888
	ds_read_b128 v[200:203], v209 offset:38912
	ds_read_b128 v[210:213], v209 offset:39936
	s_waitcnt vmcnt(8)
	s_waitcnt lgkmcnt(0)
	s_setprio 1
	s_barrier
	v_mfma_f32_16x16x32_bf16 v[124:127], v[128:131], v[160:163], v[124:127]
	v_mfma_f32_16x16x32_bf16 v[120:123], v[136:139], v[160:163], v[120:123]
	v_mfma_f32_16x16x32_bf16 v[108:111], v[128:131], v[168:171], v[108:111]
	v_mfma_f32_16x16x32_bf16 v[104:107], v[136:139], v[168:171], v[104:107]
	v_mfma_f32_16x16x32_bf16 v[92:95], v[128:131], v[192:195], v[92:95]
	v_mfma_f32_16x16x32_bf16 v[88:91], v[136:139], v[192:195], v[88:91]
	v_mfma_f32_16x16x32_bf16 v[76:79], v[128:131], v[200:203], v[76:79]
	v_mfma_f32_16x16x32_bf16 v[72:75], v[136:139], v[200:203], v[72:75]
	v_mfma_f32_16x16x32_bf16 v[124:127], v[132:135], v[164:167], v[124:127]
	v_mfma_f32_16x16x32_bf16 v[120:123], v[140:143], v[164:167], v[120:123]
	v_mfma_f32_16x16x32_bf16 v[108:111], v[132:135], v[172:175], v[108:111]
	v_mfma_f32_16x16x32_bf16 v[104:107], v[140:143], v[172:175], v[104:107]
	v_mfma_f32_16x16x32_bf16 v[92:95], v[132:135], v[196:199], v[92:95]
	v_mfma_f32_16x16x32_bf16 v[88:91], v[140:143], v[196:199], v[88:91]
	v_mfma_f32_16x16x32_bf16 v[76:79], v[132:135], v[210:213], v[76:79]
	v_mfma_f32_16x16x32_bf16 v[72:75], v[140:143], v[210:213], v[72:75]
	s_setprio 0
	s_setprio 1
	v_mfma_f32_16x16x32_bf16 v[116:119], v[144:147], v[160:163], v[116:119]
	v_mfma_f32_16x16x32_bf16 v[112:115], v[152:155], v[160:163], v[112:115]
	v_mfma_f32_16x16x32_bf16 v[100:103], v[144:147], v[168:171], v[100:103]
	v_mfma_f32_16x16x32_bf16 v[96:99], v[152:155], v[168:171], v[96:99]
	v_mfma_f32_16x16x32_bf16 v[84:87], v[144:147], v[192:195], v[84:87]
	v_mfma_f32_16x16x32_bf16 v[80:83], v[152:155], v[192:195], v[80:83]
	v_mfma_f32_16x16x32_bf16 v[68:71], v[144:147], v[200:203], v[68:71]
	v_mfma_f32_16x16x32_bf16 v[64:67], v[152:155], v[200:203], v[64:67]
	v_mfma_f32_16x16x32_bf16 v[116:119], v[148:151], v[164:167], v[116:119]
	v_mfma_f32_16x16x32_bf16 v[112:115], v[156:159], v[164:167], v[112:115]
	v_mfma_f32_16x16x32_bf16 v[100:103], v[148:151], v[172:175], v[100:103]
	v_mfma_f32_16x16x32_bf16 v[96:99], v[156:159], v[172:175], v[96:99]
	v_mfma_f32_16x16x32_bf16 v[84:87], v[148:151], v[196:199], v[84:87]
	v_mfma_f32_16x16x32_bf16 v[80:83], v[156:159], v[196:199], v[80:83]
	v_mfma_f32_16x16x32_bf16 v[68:71], v[148:151], v[210:213], v[68:71]
	v_mfma_f32_16x16x32_bf16 v[64:67], v[156:159], v[210:213], v[64:67]
	s_barrier
	s_setprio 0
	s_add_i32 s36, s70, s40
	v_lshl_add_u64 v[214:215], v[214:215], 0, s[14:15]
	s_mov_b32 m0, s36
	s_nop 0
	global_load_lds_dwordx4 v[214:215], off
	s_add_i32 m0, s36, 0x2000
	s_add_u32 s34, s34, 0x40080
	v_lshl_add_u64 v[214:215], v[216:217], 0, s[14:15]
	s_addc_u32 s35, s35, 0
	s_add_i32 s36, s71, s40
	global_load_lds_dwordx4 v[214:215], off
	v_lshl_add_u64 v[214:215], s[34:35], 0, v[178:179]
	s_mov_b32 m0, s36
	s_nop 0
	global_load_lds_dwordx4 v[214:215], off
	v_lshl_add_u64 v[214:215], s[34:35], 0, v[182:183]
	s_add_i32 m0, s36, 0x2000
	s_nop 0
	global_load_lds_dwordx4 v[214:215], off
	v_lshl_add_u64 v[214:215], v[218:219], 0, s[14:15]
	s_mov_b32 m0, s49
	s_nop 0
	global_load_lds_dwordx4 v[214:215], off
	v_lshl_add_u64 v[214:215], v[220:221], 0, s[14:15]
	s_mov_b32 m0, s50
	s_nop 0
	global_load_lds_dwordx4 v[214:215], off
	ds_read_b128 v[160:163], v209 offset:49152
	ds_read_b128 v[164:167], v209 offset:50176
	ds_read_b128 v[168:171], v209 offset:51200
	ds_read_b128 v[172:175], v209 offset:52224
	ds_read_b128 v[192:195], v209 offset:53248
	ds_read_b128 v[196:199], v209 offset:54272
	ds_read_b128 v[200:203], v209 offset:55296
	ds_read_b128 v[210:213], v209 offset:56320
	s_waitcnt vmcnt(8)
	s_waitcnt lgkmcnt(0)
	s_setprio 1
	s_barrier
	v_mfma_f32_16x16x32_bf16 v[60:63], v[128:131], v[160:163], v[60:63]
	v_mfma_f32_16x16x32_bf16 v[56:59], v[136:139], v[160:163], v[56:59]
	v_mfma_f32_16x16x32_bf16 v[44:47], v[128:131], v[168:171], v[44:47]
	v_mfma_f32_16x16x32_bf16 v[40:43], v[136:139], v[168:171], v[40:43]
	v_mfma_f32_16x16x32_bf16 v[28:31], v[128:131], v[192:195], v[28:31]
	v_mfma_f32_16x16x32_bf16 v[24:27], v[136:139], v[192:195], v[24:27]
	v_mfma_f32_16x16x32_bf16 v[12:15], v[128:131], v[200:203], v[12:15]
	v_mfma_f32_16x16x32_bf16 v[8:11], v[136:139], v[200:203], v[8:11]
	v_mfma_f32_16x16x32_bf16 v[60:63], v[132:135], v[164:167], v[60:63]
	v_mfma_f32_16x16x32_bf16 v[56:59], v[140:143], v[164:167], v[56:59]
	v_mfma_f32_16x16x32_bf16 v[44:47], v[132:135], v[172:175], v[44:47]
	v_mfma_f32_16x16x32_bf16 v[40:43], v[140:143], v[172:175], v[40:43]
	v_mfma_f32_16x16x32_bf16 v[28:31], v[132:135], v[196:199], v[28:31]
	v_mfma_f32_16x16x32_bf16 v[24:27], v[140:143], v[196:199], v[24:27]
	v_mfma_f32_16x16x32_bf16 v[12:15], v[132:135], v[210:213], v[12:15]
	v_mfma_f32_16x16x32_bf16 v[8:11], v[140:143], v[210:213], v[8:11]
	s_setprio 0
	s_setprio 1
	v_mfma_f32_16x16x32_bf16 v[52:55], v[144:147], v[160:163], v[52:55]
	v_mfma_f32_16x16x32_bf16 v[48:51], v[152:155], v[160:163], v[48:51]
	v_mfma_f32_16x16x32_bf16 v[36:39], v[144:147], v[168:171], v[36:39]
	v_mfma_f32_16x16x32_bf16 v[32:35], v[152:155], v[168:171], v[32:35]
	v_mfma_f32_16x16x32_bf16 v[20:23], v[144:147], v[192:195], v[20:23]
	v_mfma_f32_16x16x32_bf16 v[16:19], v[152:155], v[192:195], v[16:19]
	v_mfma_f32_16x16x32_bf16 v[4:7], v[144:147], v[200:203], v[4:7]
	v_mfma_f32_16x16x32_bf16 v[0:3], v[152:155], v[200:203], v[0:3]
	v_mfma_f32_16x16x32_bf16 v[52:55], v[148:151], v[164:167], v[52:55]
	v_mfma_f32_16x16x32_bf16 v[48:51], v[156:159], v[164:167], v[48:51]
	v_mfma_f32_16x16x32_bf16 v[36:39], v[148:151], v[172:175], v[36:39]
	v_mfma_f32_16x16x32_bf16 v[32:35], v[156:159], v[172:175], v[32:35]
	v_mfma_f32_16x16x32_bf16 v[20:23], v[148:151], v[196:199], v[20:23]
	v_mfma_f32_16x16x32_bf16 v[16:19], v[156:159], v[196:199], v[16:19]
	v_mfma_f32_16x16x32_bf16 v[4:7], v[148:151], v[210:213], v[4:7]
	v_mfma_f32_16x16x32_bf16 v[0:3], v[156:159], v[210:213], v[0:3]
	s_barrier
	s_setprio 0
	s_add_i32 s69, s69, 2
	s_add_u32 s30, s30, 0x100
	s_addc_u32 s31, s31, 0
	s_add_u32 s65, s65, 0x100
	s_addc_u32 s68, s68, 0
	s_cmp_gt_u32 s69, 13
	s_cbranch_scc0 .LBB0_471
	s_and_b64 vcc, exec, s[16:17]
	s_cbranch_vccz .LBB0_474
	s_barrier

.LBB0_555:
	s_add_u32 s30, s28, 0xfffc0080
	s_addc_u32 s31, s29, -1
	s_cmp_eq_u32 s63, 12
	s_cselect_b32 s35, s19, s31
	s_cselect_b32 s34, s51, s30
	s_cselect_b32 s31, s17, s62
	s_cselect_b32 s30, s60, s61
	v_lshl_add_u64 v[144:145], s[28:29], 0, v[136:137]
	s_add_i32 m0, s25, 0xc000
	s_nop 0
	global_load_lds_dwordx4 v[144:145], off
	v_lshl_add_u64 v[144:145], s[28:29], 0, v[138:139]
	s_add_i32 m0, s25, 0xe000
	s_nop 0
	global_load_lds_dwordx4 v[144:145], off
	ds_read_b128 v[154:157], v149
	ds_read_b128 v[158:161], v149 offset:1024
	ds_read_b128 v[162:165], v149 offset:2048
	ds_read_b128 v[166:169], v149 offset:3072
	ds_read_b128 v[170:173], v150
	ds_read_b128 v[174:177], v150 offset:1024
	ds_read_b128 v[178:181], v150 offset:2048
	ds_read_b128 v[182:185], v150 offset:3072
	ds_read_b128 v[186:189], v151
	ds_read_b128 v[190:193], v151 offset:1024
	ds_read_b128 v[194:197], v151 offset:2048
	ds_read_b128 v[198:201], v151 offset:3072
	ds_read_b128 v[202:205], v151 offset:4096
	ds_read_b128 v[206:209], v151 offset:5120
	ds_read_b128 v[210:213], v151 offset:6144
	ds_read_b128 v[214:217], v151 offset:7168
	s_nop 0
	s_waitcnt vmcnt(8)
	s_waitcnt lgkmcnt(0)
	s_setprio 1
	s_barrier
	v_mfma_f32_16x16x32_bf16 v[116:119], v[154:157], v[186:189], v[116:119]
	v_mfma_f32_16x16x32_bf16 v[112:115], v[162:165], v[186:189], v[112:115]
	v_mfma_f32_16x16x32_bf16 v[108:111], v[154:157], v[194:197], v[108:111]
	v_mfma_f32_16x16x32_bf16 v[100:103], v[162:165], v[194:197], v[100:103]
	v_mfma_f32_16x16x32_bf16 v[92:95], v[154:157], v[202:205], v[92:95]
	v_mfma_f32_16x16x32_bf16 v[84:87], v[162:165], v[202:205], v[84:87]
	v_mfma_f32_16x16x32_bf16 v[76:79], v[154:157], v[210:213], v[76:79]
	v_mfma_f32_16x16x32_bf16 v[68:71], v[162:165], v[210:213], v[68:71]
	v_mfma_f32_16x16x32_bf16 v[116:119], v[158:161], v[190:193], v[116:119]
	v_mfma_f32_16x16x32_bf16 v[112:115], v[166:169], v[190:193], v[112:115]
	v_mfma_f32_16x16x32_bf16 v[108:111], v[158:161], v[198:201], v[108:111]
	v_mfma_f32_16x16x32_bf16 v[100:103], v[166:169], v[198:201], v[100:103]
	v_mfma_f32_16x16x32_bf16 v[92:95], v[158:161], v[206:209], v[92:95]
	v_mfma_f32_16x16x32_bf16 v[84:87], v[166:169], v[206:209], v[84:87]
	v_mfma_f32_16x16x32_bf16 v[76:79], v[158:161], v[214:217], v[76:79]
	v_mfma_f32_16x16x32_bf16 v[68:71], v[166:169], v[214:217], v[68:71]
	s_setprio 0
	s_setprio 1
	v_mfma_f32_16x16x32_bf16 v[124:127], v[170:173], v[186:189], v[124:127]
	v_mfma_f32_16x16x32_bf16 v[120:123], v[178:181], v[186:189], v[120:123]
	v_mfma_f32_16x16x32_bf16 v[104:107], v[170:173], v[194:197], v[104:107]
	v_mfma_f32_16x16x32_bf16 v[96:99], v[178:181], v[194:197], v[96:99]
	v_mfma_f32_16x16x32_bf16 v[88:91], v[170:173], v[202:205], v[88:91]
	v_mfma_f32_16x16x32_bf16 v[80:83], v[178:181], v[202:205], v[80:83]
	v_mfma_f32_16x16x32_bf16 v[72:75], v[170:173], v[210:213], v[72:75]
	v_mfma_f32_16x16x32_bf16 v[64:67], v[178:181], v[210:213], v[64:67]
	v_mfma_f32_16x16x32_bf16 v[124:127], v[174:177], v[190:193], v[124:127]
	v_mfma_f32_16x16x32_bf16 v[120:123], v[182:185], v[190:193], v[120:123]
	v_mfma_f32_16x16x32_bf16 v[104:107], v[174:177], v[198:201], v[104:107]
	v_mfma_f32_16x16x32_bf16 v[96:99], v[182:185], v[198:201], v[96:99]
	v_mfma_f32_16x16x32_bf16 v[88:91], v[174:177], v[206:209], v[88:91]
	v_mfma_f32_16x16x32_bf16 v[80:83], v[182:185], v[206:209], v[80:83]
	v_mfma_f32_16x16x32_bf16 v[72:75], v[174:177], v[214:217], v[72:75]
	v_mfma_f32_16x16x32_bf16 v[64:67], v[182:185], v[214:217], v[64:67]
	s_barrier
	s_setprio 0
	s_add_i32 s64, s48, s36
	v_lshl_add_u64 v[144:145], s[30:31], 0, v[132:133]
	s_mov_b32 m0, s64
	s_nop 0
	global_load_lds_dwordx4 v[144:145], off
	s_add_i32 m0, s64, 0x2000
	s_add_u32 s64, s30, 0x40000
	v_lshl_add_u64 v[218:219], s[30:31], 0, v[128:129]
	s_addc_u32 s65, s31, 0
	s_add_i32 s68, s49, s36
	global_load_lds_dwordx4 v[218:219], off
	v_lshl_add_u64 v[220:221], s[64:65], 0, v[132:133]
	s_mov_b32 m0, s68
	v_lshl_add_u64 v[222:223], s[34:35], 0, v[130:131]
	global_load_lds_dwordx4 v[220:221], off
	v_lshl_add_u64 v[220:221], s[64:65], 0, v[128:129]
	s_add_i32 m0, s68, 0x2000
	s_nop 0
	global_load_lds_dwordx4 v[220:221], off
	v_lshl_add_u64 v[220:221], s[34:35], 0, v[134:135]
	s_mov_b32 m0, s25
	s_nop 0
	global_load_lds_dwordx4 v[220:221], off
	s_mov_b32 m0, s27
	s_nop 0
	global_load_lds_dwordx4 v[222:223], off
	ds_read_b128 v[186:189], v151 offset:16384
	ds_read_b128 v[190:193], v151 offset:17408
	ds_read_b128 v[194:197], v151 offset:18432
	ds_read_b128 v[198:201], v151 offset:19456
	ds_read_b128 v[202:205], v151 offset:20480
	ds_read_b128 v[206:209], v151 offset:21504
	ds_read_b128 v[210:213], v151 offset:22528
	ds_read_b128 v[214:217], v151 offset:23552
	s_nop 0
	s_waitcnt vmcnt(8)
	s_waitcnt lgkmcnt(0)
	s_setprio 1
	s_barrier
	v_mfma_f32_16x16x32_bf16 v[60:63], v[154:157], v[186:189], v[60:63]
	v_mfma_f32_16x16x32_bf16 v[52:55], v[162:165], v[186:189], v[52:55]
	v_mfma_f32_16x16x32_bf16 v[44:47], v[154:157], v[194:197], v[44:47]
	v_mfma_f32_16x16x32_bf16 v[36:39], v[162:165], v[194:197], v[36:39]
	v_mfma_f32_16x16x32_bf16 v[28:31], v[154:157], v[202:205], v[28:31]
	v_mfma_f32_16x16x32_bf16 v[20:23], v[162:165], v[202:205], v[20:23]
	v_mfma_f32_16x16x32_bf16 v[12:15], v[154:157], v[210:213], v[12:15]
	v_mfma_f32_16x16x32_bf16 v[4:7], v[162:165], v[210:213], v[4:7]
	v_mfma_f32_16x16x32_bf16 v[60:63], v[158:161], v[190:193], v[60:63]
	v_mfma_f32_16x16x32_bf16 v[52:55], v[166:169], v[190:193], v[52:55]
	v_mfma_f32_16x16x32_bf16 v[44:47], v[158:161], v[198:201], v[44:47]
	v_mfma_f32_16x16x32_bf16 v[36:39], v[166:169], v[198:201], v[36:39]
	v_mfma_f32_16x16x32_bf16 v[28:31], v[158:161], v[206:209], v[28:31]
	v_mfma_f32_16x16x32_bf16 v[20:23], v[166:169], v[206:209], v[20:23]
	v_mfma_f32_16x16x32_bf16 v[12:15], v[158:161], v[214:217], v[12:15]
	v_mfma_f32_16x16x32_bf16 v[4:7], v[166:169], v[214:217], v[4:7]
	s_setprio 0
	s_setprio 1
	v_mfma_f32_16x16x32_bf16 v[56:59], v[170:173], v[186:189], v[56:59]
	v_mfma_f32_16x16x32_bf16 v[48:51], v[178:181], v[186:189], v[48:51]
	v_mfma_f32_16x16x32_bf16 v[40:43], v[170:173], v[194:197], v[40:43]
	v_mfma_f32_16x16x32_bf16 v[32:35], v[178:181], v[194:197], v[32:35]
	v_mfma_f32_16x16x32_bf16 v[24:27], v[170:173], v[202:205], v[24:27]
	v_mfma_f32_16x16x32_bf16 v[16:19], v[178:181], v[202:205], v[16:19]
	v_mfma_f32_16x16x32_bf16 v[8:11], v[170:173], v[210:213], v[8:11]
	v_mfma_f32_16x16x32_bf16 v[0:3], v[178:181], v[210:213], v[0:3]
	v_mfma_f32_16x16x32_bf16 v[56:59], v[174:177], v[190:193], v[56:59]
	v_mfma_f32_16x16x32_bf16 v[48:51], v[182:185], v[190:193], v[48:51]
	v_mfma_f32_16x16x32_bf16 v[40:43], v[174:177], v[198:201], v[40:43]
	v_mfma_f32_16x16x32_bf16 v[32:35], v[182:185], v[198:201], v[32:35]
	v_mfma_f32_16x16x32_bf16 v[24:27], v[174:177], v[206:209], v[24:27]
	v_mfma_f32_16x16x32_bf16 v[16:19], v[182:185], v[206:209], v[16:19]
	v_mfma_f32_16x16x32_bf16 v[8:11], v[174:177], v[214:217], v[8:11]
	v_mfma_f32_16x16x32_bf16 v[0:3], v[182:185], v[214:217], v[0:3]
	s_barrier
	s_setprio 0
	s_add_i32 s64, 0, 0x18000
	s_add_i32 s65, 0, 0x1c000
	s_add_u32 s34, s34, 0x40000
	s_addc_u32 s35, s35, 0
	s_mov_b32 m0, s39
	v_lshl_add_u64 v[224:225], s[34:35], 0, v[134:135]
	global_load_lds_dwordx4 v[224:225], off
	v_lshl_add_u64 v[224:225], s[34:35], 0, v[130:131]
	s_mov_b32 m0, s40
	s_nop 0
	global_load_lds_dwordx4 v[224:225], off
	v_add_u32_e32 v153, s64, v147
	ds_read_b128 v[154:157], v153
	ds_read_b128 v[158:161], v153 offset:1024
	ds_read_b128 v[162:165], v153 offset:2048
	ds_read_b128 v[166:169], v153 offset:3072
	v_add_u32_e32 v153, s65, v147
	ds_read_b128 v[170:173], v153
	ds_read_b128 v[174:177], v153 offset:1024
	ds_read_b128 v[178:181], v153 offset:2048
	ds_read_b128 v[182:185], v153 offset:3072
	ds_read_b128 v[186:189], v151 offset:32768
	ds_read_b128 v[190:193], v151 offset:33792
	ds_read_b128 v[194:197], v151 offset:34816
	ds_read_b128 v[198:201], v151 offset:35840
	ds_read_b128 v[202:205], v151 offset:36864
	ds_read_b128 v[206:209], v151 offset:37888
	ds_read_b128 v[210:213], v151 offset:38912
	ds_read_b128 v[214:217], v151 offset:39936
	s_waitcnt vmcnt(8)
	s_waitcnt lgkmcnt(0)
	s_setprio 1
	s_barrier
	v_mfma_f32_16x16x32_bf16 v[116:119], v[154:157], v[186:189], v[116:119]
	v_mfma_f32_16x16x32_bf16 v[112:115], v[162:165], v[186:189], v[112:115]
	v_mfma_f32_16x16x32_bf16 v[108:111], v[154:157], v[194:197], v[108:111]
	v_mfma_f32_16x16x32_bf16 v[100:103], v[162:165], v[194:197], v[100:103]
	v_mfma_f32_16x16x32_bf16 v[92:95], v[154:157], v[202:205], v[92:95]
	v_mfma_f32_16x16x32_bf16 v[84:87], v[162:165], v[202:205], v[84:87]
	v_mfma_f32_16x16x32_bf16 v[76:79], v[154:157], v[210:213], v[76:79]
	v_mfma_f32_16x16x32_bf16 v[68:71], v[162:165], v[210:213], v[68:71]
	v_mfma_f32_16x16x32_bf16 v[116:119], v[158:161], v[190:193], v[116:119]
	v_mfma_f32_16x16x32_bf16 v[112:115], v[166:169], v[190:193], v[112:115]
	v_mfma_f32_16x16x32_bf16 v[108:111], v[158:161], v[198:201], v[108:111]
	v_mfma_f32_16x16x32_bf16 v[100:103], v[166:169], v[198:201], v[100:103]
	v_mfma_f32_16x16x32_bf16 v[92:95], v[158:161], v[206:209], v[92:95]
	v_mfma_f32_16x16x32_bf16 v[84:87], v[166:169], v[206:209], v[84:87]
	v_mfma_f32_16x16x32_bf16 v[76:79], v[158:161], v[214:217], v[76:79]
	v_mfma_f32_16x16x32_bf16 v[68:71], v[166:169], v[214:217], v[68:71]
	s_setprio 0
	s_setprio 1
	v_mfma_f32_16x16x32_bf16 v[124:127], v[170:173], v[186:189], v[124:127]
	v_mfma_f32_16x16x32_bf16 v[120:123], v[178:181], v[186:189], v[120:123]
	v_mfma_f32_16x16x32_bf16 v[104:107], v[170:173], v[194:197], v[104:107]
	v_mfma_f32_16x16x32_bf16 v[96:99], v[178:181], v[194:197], v[96:99]
	v_mfma_f32_16x16x32_bf16 v[88:91], v[170:173], v[202:205], v[88:91]
	v_mfma_f32_16x16x32_bf16 v[80:83], v[178:181], v[202:205], v[80:83]
	v_mfma_f32_16x16x32_bf16 v[72:75], v[170:173], v[210:213], v[72:75]
	v_mfma_f32_16x16x32_bf16 v[64:67], v[178:181], v[210:213], v[64:67]
	v_mfma_f32_16x16x32_bf16 v[124:127], v[174:177], v[190:193], v[124:127]
	v_mfma_f32_16x16x32_bf16 v[120:123], v[182:185], v[190:193], v[120:123]
	v_mfma_f32_16x16x32_bf16 v[104:107], v[174:177], v[198:201], v[104:107]
	v_mfma_f32_16x16x32_bf16 v[96:99], v[182:185], v[198:201], v[96:99]
	v_mfma_f32_16x16x32_bf16 v[88:91], v[174:177], v[206:209], v[88:91]
	v_mfma_f32_16x16x32_bf16 v[80:83], v[182:185], v[206:209], v[80:83]
	v_mfma_f32_16x16x32_bf16 v[72:75], v[174:177], v[214:217], v[72:75]
	v_mfma_f32_16x16x32_bf16 v[64:67], v[182:185], v[214:217], v[64:67]
	s_barrier
	s_setprio 0
	s_add_i32 s34, s64, s36
	v_lshl_add_u64 v[144:145], v[144:145], 0, s[12:13]
	s_mov_b32 m0, s34
	s_nop 0
	global_load_lds_dwordx4 v[144:145], off
	s_add_i32 m0, s34, 0x2000
	s_add_u32 s30, s30, 0x40080
	v_lshl_add_u64 v[144:145], v[218:219], 0, s[12:13]
	s_addc_u32 s31, s31, 0
	s_add_i32 s34, s65, s36
	global_load_lds_dwordx4 v[144:145], off
	v_lshl_add_u64 v[144:145], s[30:31], 0, v[132:133]
	s_mov_b32 m0, s34
	s_nop 0
	global_load_lds_dwordx4 v[144:145], off
	v_lshl_add_u64 v[144:145], s[30:31], 0, v[128:129]
	s_add_i32 m0, s34, 0x2000
	s_nop 0
	global_load_lds_dwordx4 v[144:145], off
	v_lshl_add_u64 v[144:145], v[220:221], 0, s[12:13]
	s_mov_b32 m0, s42
	s_nop 0
	global_load_lds_dwordx4 v[144:145], off
	v_lshl_add_u64 v[144:145], v[222:223], 0, s[12:13]
	s_mov_b32 m0, s43
	s_nop 0
	global_load_lds_dwordx4 v[144:145], off
	ds_read_b128 v[186:189], v151 offset:49152
	ds_read_b128 v[190:193], v151 offset:50176
	ds_read_b128 v[194:197], v151 offset:51200
	ds_read_b128 v[198:201], v151 offset:52224
	ds_read_b128 v[202:205], v151 offset:53248
	ds_read_b128 v[206:209], v151 offset:54272
	ds_read_b128 v[210:213], v151 offset:55296
	ds_read_b128 v[214:217], v151 offset:56320
	s_waitcnt vmcnt(8)
	s_waitcnt lgkmcnt(0)
	s_setprio 1
	s_barrier
	v_mfma_f32_16x16x32_bf16 v[60:63], v[154:157], v[186:189], v[60:63]
	v_mfma_f32_16x16x32_bf16 v[52:55], v[162:165], v[186:189], v[52:55]
	v_mfma_f32_16x16x32_bf16 v[44:47], v[154:157], v[194:197], v[44:47]
	v_mfma_f32_16x16x32_bf16 v[36:39], v[162:165], v[194:197], v[36:39]
	v_mfma_f32_16x16x32_bf16 v[28:31], v[154:157], v[202:205], v[28:31]
	v_mfma_f32_16x16x32_bf16 v[20:23], v[162:165], v[202:205], v[20:23]
	v_mfma_f32_16x16x32_bf16 v[12:15], v[154:157], v[210:213], v[12:15]
	v_mfma_f32_16x16x32_bf16 v[4:7], v[162:165], v[210:213], v[4:7]
	v_mfma_f32_16x16x32_bf16 v[60:63], v[158:161], v[190:193], v[60:63]
	v_mfma_f32_16x16x32_bf16 v[52:55], v[166:169], v[190:193], v[52:55]
	v_mfma_f32_16x16x32_bf16 v[44:47], v[158:161], v[198:201], v[44:47]
	v_mfma_f32_16x16x32_bf16 v[36:39], v[166:169], v[198:201], v[36:39]
	v_mfma_f32_16x16x32_bf16 v[28:31], v[158:161], v[206:209], v[28:31]
	v_mfma_f32_16x16x32_bf16 v[20:23], v[166:169], v[206:209], v[20:23]
	v_mfma_f32_16x16x32_bf16 v[12:15], v[158:161], v[214:217], v[12:15]
	v_mfma_f32_16x16x32_bf16 v[4:7], v[166:169], v[214:217], v[4:7]
	s_setprio 0
	s_setprio 1
	v_mfma_f32_16x16x32_bf16 v[56:59], v[170:173], v[186:189], v[56:59]
	v_mfma_f32_16x16x32_bf16 v[48:51], v[178:181], v[186:189], v[48:51]
	v_mfma_f32_16x16x32_bf16 v[40:43], v[170:173], v[194:197], v[40:43]
	v_mfma_f32_16x16x32_bf16 v[32:35], v[178:181], v[194:197], v[32:35]
	v_mfma_f32_16x16x32_bf16 v[24:27], v[170:173], v[202:205], v[24:27]
	v_mfma_f32_16x16x32_bf16 v[16:19], v[178:181], v[202:205], v[16:19]
	v_mfma_f32_16x16x32_bf16 v[8:11], v[170:173], v[210:213], v[8:11]
	v_mfma_f32_16x16x32_bf16 v[0:3], v[178:181], v[210:213], v[0:3]
	v_mfma_f32_16x16x32_bf16 v[56:59], v[174:177], v[190:193], v[56:59]
	v_mfma_f32_16x16x32_bf16 v[48:51], v[182:185], v[190:193], v[48:51]
	v_mfma_f32_16x16x32_bf16 v[40:43], v[174:177], v[198:201], v[40:43]
	v_mfma_f32_16x16x32_bf16 v[32:35], v[182:185], v[198:201], v[32:35]
	v_mfma_f32_16x16x32_bf16 v[24:27], v[174:177], v[206:209], v[24:27]
	v_mfma_f32_16x16x32_bf16 v[16:19], v[182:185], v[206:209], v[16:19]
	v_mfma_f32_16x16x32_bf16 v[8:11], v[174:177], v[214:217], v[8:11]
	v_mfma_f32_16x16x32_bf16 v[0:3], v[182:185], v[214:217], v[0:3]
	s_barrier
	s_setprio 0
	s_add_i32 s63, s63, 2
	s_add_u32 s28, s28, 0x100
	s_addc_u32 s29, s29, 0
	s_add_u32 s61, s61, 0x100
	s_addc_u32 s62, s62, 0
	s_cmp_gt_u32 s63, 13
	s_cbranch_scc0 .LBB0_555
	s_and_b64 vcc, exec, s[14:15]
	s_cbranch_vccz .LBB0_558
	s_barrier

.LBB0_637:
	s_add_u32 s22, s20, 0x100
	s_addc_u32 s23, s21, 0
	s_cmp_eq_u32 s61, 40
	s_cselect_b32 s27, s9, s23
	s_cselect_b32 s26, s8, s22
	s_cselect_b32 s25, s19, s60
	s_cselect_b32 s24, s18, s51
	v_lshl_add_u64 v[206:207], s[20:21], 0, v[200:201]
	s_add_i32 m0, s29, 0xc000
	s_nop 0
	global_load_lds_dwordx4 v[206:207], off
	v_lshl_add_u64 v[206:207], s[20:21], 0, v[202:203]
	s_add_i32 m0, s29, 0xe000
	s_nop 0
	global_load_lds_dwordx4 v[206:207], off
	ds_read_b128 v[120:123], v247
	ds_read_b128 v[124:127], v247 offset:1024
	ds_read_b128 v[128:131], v247 offset:2048
	ds_read_b128 v[132:135], v247 offset:3072
	ds_read_b128 v[140:143], v248
	ds_read_b128 v[148:151], v248 offset:1024
	ds_read_b128 v[152:155], v248 offset:2048
	ds_read_b128 v[156:159], v248 offset:3072
	ds_read_b128 v[160:163], v249
	ds_read_b128 v[164:167], v249 offset:1024
	ds_read_b128 v[168:171], v249 offset:2048
	ds_read_b128 v[172:175], v249 offset:3072
	ds_read_b128 v[176:179], v249 offset:4096
	ds_read_b128 v[180:183], v249 offset:5120
	ds_read_b128 v[184:187], v249 offset:6144
	ds_read_b128 v[188:191], v249 offset:7168
	s_nop 0
	s_waitcnt vmcnt(8)
	s_waitcnt lgkmcnt(0)
	s_setprio 1
	s_barrier
	v_mfma_f32_16x16x32_bf16 v[144:147], v[120:123], v[160:163], v[144:147]
	v_mfma_f32_16x16x32_bf16 v[136:139], v[128:131], v[160:163], v[136:139]
	v_mfma_f32_16x16x32_bf16 v[108:111], v[120:123], v[168:171], v[108:111]
	v_mfma_f32_16x16x32_bf16 v[104:107], v[128:131], v[168:171], v[104:107]
	v_mfma_f32_16x16x32_bf16 v[92:95], v[120:123], v[176:179], v[92:95]
	v_mfma_f32_16x16x32_bf16 v[88:91], v[128:131], v[176:179], v[88:91]
	v_mfma_f32_16x16x32_bf16 v[76:79], v[120:123], v[184:187], v[76:79]
	v_mfma_f32_16x16x32_bf16 v[72:75], v[128:131], v[184:187], v[72:75]
	v_mfma_f32_16x16x32_bf16 v[144:147], v[124:127], v[164:167], v[144:147]
	v_mfma_f32_16x16x32_bf16 v[136:139], v[132:135], v[164:167], v[136:139]
	v_mfma_f32_16x16x32_bf16 v[108:111], v[124:127], v[172:175], v[108:111]
	v_mfma_f32_16x16x32_bf16 v[104:107], v[132:135], v[172:175], v[104:107]
	v_mfma_f32_16x16x32_bf16 v[92:95], v[124:127], v[180:183], v[92:95]
	v_mfma_f32_16x16x32_bf16 v[88:91], v[132:135], v[180:183], v[88:91]
	v_mfma_f32_16x16x32_bf16 v[76:79], v[124:127], v[188:191], v[76:79]
	v_mfma_f32_16x16x32_bf16 v[72:75], v[132:135], v[188:191], v[72:75]
	s_setprio 0
	s_setprio 1
	v_mfma_f32_16x16x32_bf16 v[116:119], v[140:143], v[160:163], v[116:119]
	v_mfma_f32_16x16x32_bf16 v[112:115], v[152:155], v[160:163], v[112:115]
	v_mfma_f32_16x16x32_bf16 v[100:103], v[140:143], v[168:171], v[100:103]
	v_mfma_f32_16x16x32_bf16 v[96:99], v[152:155], v[168:171], v[96:99]
	v_mfma_f32_16x16x32_bf16 v[84:87], v[140:143], v[176:179], v[84:87]
	v_mfma_f32_16x16x32_bf16 v[80:83], v[152:155], v[176:179], v[80:83]
	v_mfma_f32_16x16x32_bf16 v[68:71], v[140:143], v[184:187], v[68:71]
	v_mfma_f32_16x16x32_bf16 v[64:67], v[152:155], v[184:187], v[64:67]
	v_mfma_f32_16x16x32_bf16 v[116:119], v[148:151], v[164:167], v[116:119]
	v_mfma_f32_16x16x32_bf16 v[112:115], v[156:159], v[164:167], v[112:115]
	v_mfma_f32_16x16x32_bf16 v[100:103], v[148:151], v[172:175], v[100:103]
	v_mfma_f32_16x16x32_bf16 v[96:99], v[156:159], v[172:175], v[96:99]
	v_mfma_f32_16x16x32_bf16 v[84:87], v[148:151], v[180:183], v[84:87]
	v_mfma_f32_16x16x32_bf16 v[80:83], v[156:159], v[180:183], v[80:83]
	v_mfma_f32_16x16x32_bf16 v[68:71], v[148:151], v[188:191], v[68:71]
	v_mfma_f32_16x16x32_bf16 v[64:67], v[156:159], v[188:191], v[64:67]
	s_barrier
	s_setprio 0
	s_add_i32 s20, s43, s28
	v_lshl_add_u64 v[206:207], s[24:25], 0, v[194:195]
	s_mov_b32 m0, s20
	s_nop 0
	global_load_lds_dwordx4 v[206:207], off
	s_add_i32 m0, s20, 0x2000
	s_add_u32 s20, s24, 0xb0000
	v_lshl_add_u64 v[208:209], s[24:25], 0, v[198:199]
	s_addc_u32 s21, s25, 0
	s_add_i32 s62, s46, s28
	global_load_lds_dwordx4 v[208:209], off
	v_lshl_add_u64 v[210:211], s[20:21], 0, v[194:195]
	s_mov_b32 m0, s62
	v_lshl_add_u64 v[212:213], s[26:27], 0, v[196:197]
	global_load_lds_dwordx4 v[210:211], off
	v_lshl_add_u64 v[210:211], s[20:21], 0, v[198:199]
	s_add_i32 m0, s62, 0x2000
	s_nop 0
	global_load_lds_dwordx4 v[210:211], off
	v_lshl_add_u64 v[210:211], s[26:27], 0, v[192:193]
	s_mov_b32 m0, s29
	s_nop 0
	global_load_lds_dwordx4 v[210:211], off
	s_mov_b32 m0, s30
	s_nop 0
	global_load_lds_dwordx4 v[212:213], off
	ds_read_b128 v[160:163], v249 offset:16384
	ds_read_b128 v[164:167], v249 offset:17408
	ds_read_b128 v[168:171], v249 offset:18432
	ds_read_b128 v[172:175], v249 offset:19456
	ds_read_b128 v[176:179], v249 offset:20480
	ds_read_b128 v[180:183], v249 offset:21504
	ds_read_b128 v[184:187], v249 offset:22528
	ds_read_b128 v[188:191], v249 offset:23552
	s_nop 0
	s_waitcnt vmcnt(8)
	s_waitcnt lgkmcnt(0)
	s_setprio 1
	s_barrier
	v_mfma_f32_16x16x32_bf16 v[60:63], v[120:123], v[160:163], v[60:63]
	v_mfma_f32_16x16x32_bf16 v[56:59], v[128:131], v[160:163], v[56:59]
	v_mfma_f32_16x16x32_bf16 v[44:47], v[120:123], v[168:171], v[44:47]
	v_mfma_f32_16x16x32_bf16 v[40:43], v[128:131], v[168:171], v[40:43]
	v_mfma_f32_16x16x32_bf16 v[28:31], v[120:123], v[176:179], v[28:31]
	v_mfma_f32_16x16x32_bf16 v[24:27], v[128:131], v[176:179], v[24:27]
	v_mfma_f32_16x16x32_bf16 v[12:15], v[120:123], v[184:187], v[12:15]
	v_mfma_f32_16x16x32_bf16 v[8:11], v[128:131], v[184:187], v[8:11]
	v_mfma_f32_16x16x32_bf16 v[60:63], v[124:127], v[164:167], v[60:63]
	v_mfma_f32_16x16x32_bf16 v[56:59], v[132:135], v[164:167], v[56:59]
	v_mfma_f32_16x16x32_bf16 v[44:47], v[124:127], v[172:175], v[44:47]
	v_mfma_f32_16x16x32_bf16 v[40:43], v[132:135], v[172:175], v[40:43]
	v_mfma_f32_16x16x32_bf16 v[28:31], v[124:127], v[180:183], v[28:31]
	v_mfma_f32_16x16x32_bf16 v[24:27], v[132:135], v[180:183], v[24:27]
	v_mfma_f32_16x16x32_bf16 v[12:15], v[124:127], v[188:191], v[12:15]
	v_mfma_f32_16x16x32_bf16 v[8:11], v[132:135], v[188:191], v[8:11]
	s_setprio 0
	s_setprio 1
	v_mfma_f32_16x16x32_bf16 v[52:55], v[140:143], v[160:163], v[52:55]
	v_mfma_f32_16x16x32_bf16 v[48:51], v[152:155], v[160:163], v[48:51]
	v_mfma_f32_16x16x32_bf16 v[36:39], v[140:143], v[168:171], v[36:39]
	v_mfma_f32_16x16x32_bf16 v[32:35], v[152:155], v[168:171], v[32:35]
	v_mfma_f32_16x16x32_bf16 v[20:23], v[140:143], v[176:179], v[20:23]
	v_mfma_f32_16x16x32_bf16 v[16:19], v[152:155], v[176:179], v[16:19]
	v_mfma_f32_16x16x32_bf16 v[4:7], v[140:143], v[184:187], v[4:7]
	v_mfma_f32_16x16x32_bf16 v[0:3], v[152:155], v[184:187], v[0:3]
	v_mfma_f32_16x16x32_bf16 v[52:55], v[148:151], v[164:167], v[52:55]
	v_mfma_f32_16x16x32_bf16 v[48:51], v[156:159], v[164:167], v[48:51]
	v_mfma_f32_16x16x32_bf16 v[36:39], v[148:151], v[172:175], v[36:39]
	v_mfma_f32_16x16x32_bf16 v[32:35], v[156:159], v[172:175], v[32:35]
	v_mfma_f32_16x16x32_bf16 v[20:23], v[148:151], v[180:183], v[20:23]
	v_mfma_f32_16x16x32_bf16 v[16:19], v[156:159], v[180:183], v[16:19]
	v_mfma_f32_16x16x32_bf16 v[4:7], v[148:151], v[188:191], v[4:7]
	v_mfma_f32_16x16x32_bf16 v[0:3], v[156:159], v[188:191], v[0:3]
	s_barrier
	s_setprio 0
	s_add_i32 s62, 0, 0x18000
	s_add_i32 s63, 0, 0x1c000
	s_add_u32 s20, s26, 0xb0000
	s_addc_u32 s21, s27, 0
	s_mov_b32 m0, s31
	v_lshl_add_u64 v[214:215], s[20:21], 0, v[192:193]
	global_load_lds_dwordx4 v[214:215], off
	v_lshl_add_u64 v[214:215], s[20:21], 0, v[196:197]
	s_mov_b32 m0, s34
	s_nop 0
	global_load_lds_dwordx4 v[214:215], off
	v_add_u32_e32 v132, s62, v246
	v_add_u32_e32 v156, s63, v246
	ds_read_b128 v[120:123], v132
	ds_read_b128 v[124:127], v132 offset:1024
	ds_read_b128 v[128:131], v132 offset:2048
	ds_read_b128 v[132:135], v132 offset:3072
	ds_read_b128 v[140:143], v156
	ds_read_b128 v[148:151], v156 offset:1024
	ds_read_b128 v[152:155], v156 offset:2048
	ds_read_b128 v[156:159], v156 offset:3072
	ds_read_b128 v[160:163], v249 offset:32768
	ds_read_b128 v[164:167], v249 offset:33792
	ds_read_b128 v[168:171], v249 offset:34816
	ds_read_b128 v[172:175], v249 offset:35840
	ds_read_b128 v[176:179], v249 offset:36864
	ds_read_b128 v[180:183], v249 offset:37888
	ds_read_b128 v[184:187], v249 offset:38912
	ds_read_b128 v[188:191], v249 offset:39936
	s_waitcnt vmcnt(8)
	s_waitcnt lgkmcnt(0)
	s_setprio 1
	s_barrier
	v_mfma_f32_16x16x32_bf16 v[144:147], v[120:123], v[160:163], v[144:147]
	v_mfma_f32_16x16x32_bf16 v[136:139], v[128:131], v[160:163], v[136:139]
	v_mfma_f32_16x16x32_bf16 v[108:111], v[120:123], v[168:171], v[108:111]
	v_mfma_f32_16x16x32_bf16 v[104:107], v[128:131], v[168:171], v[104:107]
	v_mfma_f32_16x16x32_bf16 v[92:95], v[120:123], v[176:179], v[92:95]
	v_mfma_f32_16x16x32_bf16 v[88:91], v[128:131], v[176:179], v[88:91]
	v_mfma_f32_16x16x32_bf16 v[76:79], v[120:123], v[184:187], v[76:79]
	v_mfma_f32_16x16x32_bf16 v[72:75], v[128:131], v[184:187], v[72:75]
	v_mfma_f32_16x16x32_bf16 v[144:147], v[124:127], v[164:167], v[144:147]
	v_mfma_f32_16x16x32_bf16 v[136:139], v[132:135], v[164:167], v[136:139]
	v_mfma_f32_16x16x32_bf16 v[108:111], v[124:127], v[172:175], v[108:111]
	v_mfma_f32_16x16x32_bf16 v[104:107], v[132:135], v[172:175], v[104:107]
	v_mfma_f32_16x16x32_bf16 v[92:95], v[124:127], v[180:183], v[92:95]
	v_mfma_f32_16x16x32_bf16 v[88:91], v[132:135], v[180:183], v[88:91]
	v_mfma_f32_16x16x32_bf16 v[76:79], v[124:127], v[188:191], v[76:79]
	v_mfma_f32_16x16x32_bf16 v[72:75], v[132:135], v[188:191], v[72:75]
	s_setprio 0
	s_setprio 1
	v_mfma_f32_16x16x32_bf16 v[116:119], v[140:143], v[160:163], v[116:119]
	v_mfma_f32_16x16x32_bf16 v[112:115], v[152:155], v[160:163], v[112:115]
	v_mfma_f32_16x16x32_bf16 v[100:103], v[140:143], v[168:171], v[100:103]
	v_mfma_f32_16x16x32_bf16 v[96:99], v[152:155], v[168:171], v[96:99]
	v_mfma_f32_16x16x32_bf16 v[84:87], v[140:143], v[176:179], v[84:87]
	v_mfma_f32_16x16x32_bf16 v[80:83], v[152:155], v[176:179], v[80:83]
	v_mfma_f32_16x16x32_bf16 v[68:71], v[140:143], v[184:187], v[68:71]
	v_mfma_f32_16x16x32_bf16 v[64:67], v[152:155], v[184:187], v[64:67]
	v_mfma_f32_16x16x32_bf16 v[116:119], v[148:151], v[164:167], v[116:119]
	v_mfma_f32_16x16x32_bf16 v[112:115], v[156:159], v[164:167], v[112:115]
	v_mfma_f32_16x16x32_bf16 v[100:103], v[148:151], v[172:175], v[100:103]
	v_mfma_f32_16x16x32_bf16 v[96:99], v[156:159], v[172:175], v[96:99]
	v_mfma_f32_16x16x32_bf16 v[84:87], v[148:151], v[180:183], v[84:87]
	v_mfma_f32_16x16x32_bf16 v[80:83], v[156:159], v[180:183], v[80:83]
	v_mfma_f32_16x16x32_bf16 v[68:71], v[148:151], v[188:191], v[68:71]
	v_mfma_f32_16x16x32_bf16 v[64:67], v[156:159], v[188:191], v[64:67]
	s_barrier
	s_setprio 0
	s_add_i32 s20, s62, s28
	v_lshl_add_u64 v[206:207], v[206:207], 0, s[14:15]
	s_mov_b32 m0, s20
	s_nop 0
	global_load_lds_dwordx4 v[206:207], off
	s_add_i32 m0, s20, 0x2000
	s_add_u32 s20, s24, 0xb0080
	v_lshl_add_u64 v[206:207], v[208:209], 0, s[14:15]
	s_addc_u32 s21, s25, 0
	s_add_i32 s24, s63, s28
	global_load_lds_dwordx4 v[206:207], off
	v_lshl_add_u64 v[206:207], s[20:21], 0, v[194:195]
	s_mov_b32 m0, s24
	s_nop 0
	global_load_lds_dwordx4 v[206:207], off
	v_lshl_add_u64 v[206:207], s[20:21], 0, v[198:199]
	s_add_i32 m0, s24, 0x2000
	s_nop 0
	global_load_lds_dwordx4 v[206:207], off
	v_lshl_add_u64 v[206:207], v[210:211], 0, s[14:15]
	s_mov_b32 m0, s38
	s_nop 0
	global_load_lds_dwordx4 v[206:207], off
	v_lshl_add_u64 v[206:207], v[212:213], 0, s[14:15]
	s_mov_b32 m0, s39
	s_nop 0
	global_load_lds_dwordx4 v[206:207], off
	ds_read_b128 v[160:163], v249 offset:49152
	ds_read_b128 v[164:167], v249 offset:50176
	ds_read_b128 v[168:171], v249 offset:51200
	ds_read_b128 v[172:175], v249 offset:52224
	ds_read_b128 v[176:179], v249 offset:53248
	ds_read_b128 v[180:183], v249 offset:54272
	ds_read_b128 v[184:187], v249 offset:55296
	ds_read_b128 v[188:191], v249 offset:56320
	s_waitcnt vmcnt(8)
	s_waitcnt lgkmcnt(0)
	s_setprio 1
	s_barrier
	v_mfma_f32_16x16x32_bf16 v[60:63], v[120:123], v[160:163], v[60:63]
	v_mfma_f32_16x16x32_bf16 v[56:59], v[128:131], v[160:163], v[56:59]
	v_mfma_f32_16x16x32_bf16 v[44:47], v[120:123], v[168:171], v[44:47]
	v_mfma_f32_16x16x32_bf16 v[40:43], v[128:131], v[168:171], v[40:43]
	v_mfma_f32_16x16x32_bf16 v[28:31], v[120:123], v[176:179], v[28:31]
	v_mfma_f32_16x16x32_bf16 v[24:27], v[128:131], v[176:179], v[24:27]
	v_mfma_f32_16x16x32_bf16 v[12:15], v[120:123], v[184:187], v[12:15]
	v_mfma_f32_16x16x32_bf16 v[8:11], v[128:131], v[184:187], v[8:11]
	v_mfma_f32_16x16x32_bf16 v[60:63], v[124:127], v[164:167], v[60:63]
	v_mfma_f32_16x16x32_bf16 v[56:59], v[132:135], v[164:167], v[56:59]
	v_mfma_f32_16x16x32_bf16 v[44:47], v[124:127], v[172:175], v[44:47]
	v_mfma_f32_16x16x32_bf16 v[40:43], v[132:135], v[172:175], v[40:43]
	v_mfma_f32_16x16x32_bf16 v[28:31], v[124:127], v[180:183], v[28:31]
	v_mfma_f32_16x16x32_bf16 v[24:27], v[132:135], v[180:183], v[24:27]
	v_mfma_f32_16x16x32_bf16 v[12:15], v[124:127], v[188:191], v[12:15]
	v_mfma_f32_16x16x32_bf16 v[8:11], v[132:135], v[188:191], v[8:11]
	s_setprio 0
	s_setprio 1
	v_mfma_f32_16x16x32_bf16 v[52:55], v[140:143], v[160:163], v[52:55]
	v_mfma_f32_16x16x32_bf16 v[48:51], v[152:155], v[160:163], v[48:51]
	v_mfma_f32_16x16x32_bf16 v[36:39], v[140:143], v[168:171], v[36:39]
	v_mfma_f32_16x16x32_bf16 v[32:35], v[152:155], v[168:171], v[32:35]
	v_mfma_f32_16x16x32_bf16 v[20:23], v[140:143], v[176:179], v[20:23]
	v_mfma_f32_16x16x32_bf16 v[16:19], v[152:155], v[176:179], v[16:19]
	v_mfma_f32_16x16x32_bf16 v[4:7], v[140:143], v[184:187], v[4:7]
	v_mfma_f32_16x16x32_bf16 v[0:3], v[152:155], v[184:187], v[0:3]
	v_mfma_f32_16x16x32_bf16 v[52:55], v[148:151], v[164:167], v[52:55]
	v_mfma_f32_16x16x32_bf16 v[48:51], v[156:159], v[164:167], v[48:51]
	v_mfma_f32_16x16x32_bf16 v[36:39], v[148:151], v[172:175], v[36:39]
	v_mfma_f32_16x16x32_bf16 v[32:35], v[156:159], v[172:175], v[32:35]
	v_mfma_f32_16x16x32_bf16 v[20:23], v[148:151], v[180:183], v[20:23]
	v_mfma_f32_16x16x32_bf16 v[16:19], v[156:159], v[180:183], v[16:19]
	v_mfma_f32_16x16x32_bf16 v[4:7], v[148:151], v[188:191], v[4:7]
	v_mfma_f32_16x16x32_bf16 v[0:3], v[156:159], v[188:191], v[0:3]
	s_barrier
	s_setprio 0
	s_add_i32 s61, s61, 2
	s_add_u32 s51, s51, 0x100
	s_addc_u32 s60, s60, 0
	s_cmp_gt_u32 s61, 41
	s_mov_b64 s[20:21], s[22:23]
	s_cbranch_scc0 .LBB0_637
	s_and_b64 vcc, exec, s[16:17]
	s_cbranch_vccz .LBB0_640
	s_barrier

.LBB0_723:
	s_add_u32 s62, s48, 0xfffc0080
	s_addc_u32 s63, s49, -1
	s_cmp_eq_u32 s93, 12
	s_cselect_b32 s65, s9, s63
	s_cselect_b32 s64, s41, s62
	s_cselect_b32 s63, s39, s61
	s_cselect_b32 s62, s51, s60
	v_lshl_add_u64 v[192:193], s[48:49], 0, v[214:215]
	s_add_i32 m0, s69, 0xc000
	s_nop 0
	global_load_lds_dwordx4 v[192:193], off
	v_lshl_add_u64 v[192:193], s[48:49], 0, v[216:217]
	s_add_i32 m0, s69, 0xe000
	s_nop 0
	global_load_lds_dwordx4 v[192:193], off
	ds_read_b128 v[128:131], v235
	ds_read_b128 v[132:135], v235 offset:1024
	ds_read_b128 v[136:139], v235 offset:2048
	ds_read_b128 v[140:143], v235 offset:3072
	ds_read_b128 v[144:147], v236
	ds_read_b128 v[148:151], v236 offset:1024
	ds_read_b128 v[152:155], v236 offset:2048
	ds_read_b128 v[156:159], v236 offset:3072
	ds_read_b128 v[160:163], v237
	ds_read_b128 v[164:167], v237 offset:1024
	ds_read_b128 v[168:171], v237 offset:2048
	ds_read_b128 v[172:175], v237 offset:3072
	ds_read_b128 v[176:179], v237 offset:4096
	ds_read_b128 v[180:183], v237 offset:5120
	ds_read_b128 v[184:187], v237 offset:6144
	ds_read_b128 v[188:191], v237 offset:7168
	s_nop 0
	s_waitcnt vmcnt(8)
	s_waitcnt lgkmcnt(0)
	s_setprio 1
	s_barrier
	v_mfma_f32_16x16x32_bf16 v[124:127], v[128:131], v[160:163], v[124:127]
	v_mfma_f32_16x16x32_bf16 v[120:123], v[136:139], v[160:163], v[120:123]
	v_mfma_f32_16x16x32_bf16 v[116:119], v[128:131], v[168:171], v[116:119]
	v_mfma_f32_16x16x32_bf16 v[112:115], v[136:139], v[168:171], v[112:115]
	v_mfma_f32_16x16x32_bf16 v[108:111], v[128:131], v[176:179], v[108:111]
	v_mfma_f32_16x16x32_bf16 v[100:103], v[136:139], v[176:179], v[100:103]
	v_mfma_f32_16x16x32_bf16 v[92:95], v[128:131], v[184:187], v[92:95]
	v_mfma_f32_16x16x32_bf16 v[80:83], v[136:139], v[184:187], v[80:83]
	v_mfma_f32_16x16x32_bf16 v[124:127], v[132:135], v[164:167], v[124:127]
	v_mfma_f32_16x16x32_bf16 v[120:123], v[140:143], v[164:167], v[120:123]
	v_mfma_f32_16x16x32_bf16 v[116:119], v[132:135], v[172:175], v[116:119]
	v_mfma_f32_16x16x32_bf16 v[112:115], v[140:143], v[172:175], v[112:115]
	v_mfma_f32_16x16x32_bf16 v[108:111], v[132:135], v[180:183], v[108:111]
	v_mfma_f32_16x16x32_bf16 v[100:103], v[140:143], v[180:183], v[100:103]
	v_mfma_f32_16x16x32_bf16 v[92:95], v[132:135], v[188:191], v[92:95]
	v_mfma_f32_16x16x32_bf16 v[80:83], v[140:143], v[188:191], v[80:83]
	s_setprio 0
	s_setprio 1
	v_mfma_f32_16x16x32_bf16 v[104:107], v[144:147], v[160:163], v[104:107]
	v_mfma_f32_16x16x32_bf16 v[96:99], v[152:155], v[160:163], v[96:99]
	v_mfma_f32_16x16x32_bf16 v[88:91], v[144:147], v[168:171], v[88:91]
	v_mfma_f32_16x16x32_bf16 v[84:87], v[152:155], v[168:171], v[84:87]
	v_mfma_f32_16x16x32_bf16 v[76:79], v[144:147], v[176:179], v[76:79]
	v_mfma_f32_16x16x32_bf16 v[72:75], v[152:155], v[176:179], v[72:75]
	v_mfma_f32_16x16x32_bf16 v[68:71], v[144:147], v[184:187], v[68:71]
	v_mfma_f32_16x16x32_bf16 v[64:67], v[152:155], v[184:187], v[64:67]
	v_mfma_f32_16x16x32_bf16 v[104:107], v[148:151], v[164:167], v[104:107]
	v_mfma_f32_16x16x32_bf16 v[96:99], v[156:159], v[164:167], v[96:99]
	v_mfma_f32_16x16x32_bf16 v[88:91], v[148:151], v[172:175], v[88:91]
	v_mfma_f32_16x16x32_bf16 v[84:87], v[156:159], v[172:175], v[84:87]
	v_mfma_f32_16x16x32_bf16 v[76:79], v[148:151], v[180:183], v[76:79]
	v_mfma_f32_16x16x32_bf16 v[72:75], v[156:159], v[180:183], v[72:75]
	v_mfma_f32_16x16x32_bf16 v[68:71], v[148:151], v[188:191], v[68:71]
	v_mfma_f32_16x16x32_bf16 v[64:67], v[156:159], v[188:191], v[64:67]
	s_barrier
	s_setprio 0
	s_add_i32 s94, s88, s68
	v_lshl_add_u64 v[192:193], s[62:63], 0, v[208:209]
	s_mov_b32 m0, s94
	s_nop 0
	global_load_lds_dwordx4 v[192:193], off
	s_add_i32 m0, s94, 0x2000
	s_add_u32 s94, s62, 0x40000
	v_lshl_add_u64 v[194:195], s[62:63], 0, v[212:213]
	s_addc_u32 s95, s63, 0
	s_add_i32 s96, s89, s68
	global_load_lds_dwordx4 v[194:195], off
	v_lshl_add_u64 v[196:197], s[94:95], 0, v[208:209]
	s_mov_b32 m0, s96
	v_lshl_add_u64 v[198:199], s[64:65], 0, v[210:211]
	global_load_lds_dwordx4 v[196:197], off
	v_lshl_add_u64 v[196:197], s[94:95], 0, v[212:213]
	s_add_i32 m0, s96, 0x2000
	s_nop 0
	global_load_lds_dwordx4 v[196:197], off
	v_lshl_add_u64 v[196:197], s[64:65], 0, v[206:207]
	s_mov_b32 m0, s69
	s_nop 0
	global_load_lds_dwordx4 v[196:197], off
	s_mov_b32 m0, s70
	s_nop 0
	global_load_lds_dwordx4 v[198:199], off
	ds_read_b128 v[160:163], v237 offset:16384
	ds_read_b128 v[164:167], v237 offset:17408
	ds_read_b128 v[168:171], v237 offset:18432
	ds_read_b128 v[172:175], v237 offset:19456
	ds_read_b128 v[176:179], v237 offset:20480
	ds_read_b128 v[180:183], v237 offset:21504
	ds_read_b128 v[184:187], v237 offset:22528
	ds_read_b128 v[188:191], v237 offset:23552
	s_nop 0
	s_waitcnt vmcnt(8)
	s_waitcnt lgkmcnt(0)
	s_setprio 1
	s_barrier
	v_mfma_f32_16x16x32_bf16 v[60:63], v[128:131], v[160:163], v[60:63]
	v_mfma_f32_16x16x32_bf16 v[56:59], v[136:139], v[160:163], v[56:59]
	v_mfma_f32_16x16x32_bf16 v[48:51], v[128:131], v[168:171], v[48:51]
	v_mfma_f32_16x16x32_bf16 v[40:43], v[136:139], v[168:171], v[40:43]
	v_mfma_f32_16x16x32_bf16 v[32:35], v[128:131], v[176:179], v[32:35]
	v_mfma_f32_16x16x32_bf16 v[24:27], v[136:139], v[176:179], v[24:27]
	v_mfma_f32_16x16x32_bf16 v[16:19], v[128:131], v[184:187], v[16:19]
	v_mfma_f32_16x16x32_bf16 v[8:11], v[136:139], v[184:187], v[8:11]
	v_mfma_f32_16x16x32_bf16 v[60:63], v[132:135], v[164:167], v[60:63]
	v_mfma_f32_16x16x32_bf16 v[56:59], v[140:143], v[164:167], v[56:59]
	v_mfma_f32_16x16x32_bf16 v[48:51], v[132:135], v[172:175], v[48:51]
	v_mfma_f32_16x16x32_bf16 v[40:43], v[140:143], v[172:175], v[40:43]
	v_mfma_f32_16x16x32_bf16 v[32:35], v[132:135], v[180:183], v[32:35]
	v_mfma_f32_16x16x32_bf16 v[24:27], v[140:143], v[180:183], v[24:27]
	v_mfma_f32_16x16x32_bf16 v[16:19], v[132:135], v[188:191], v[16:19]
	v_mfma_f32_16x16x32_bf16 v[8:11], v[140:143], v[188:191], v[8:11]
	s_setprio 0
	s_setprio 1
	v_mfma_f32_16x16x32_bf16 v[52:55], v[144:147], v[160:163], v[52:55]
	v_mfma_f32_16x16x32_bf16 v[44:47], v[152:155], v[160:163], v[44:47]
	v_mfma_f32_16x16x32_bf16 v[36:39], v[144:147], v[168:171], v[36:39]
	v_mfma_f32_16x16x32_bf16 v[28:31], v[152:155], v[168:171], v[28:31]
	v_mfma_f32_16x16x32_bf16 v[20:23], v[144:147], v[176:179], v[20:23]
	v_mfma_f32_16x16x32_bf16 v[12:15], v[152:155], v[176:179], v[12:15]
	v_mfma_f32_16x16x32_bf16 v[4:7], v[144:147], v[184:187], v[4:7]
	v_mfma_f32_16x16x32_bf16 v[0:3], v[152:155], v[184:187], v[0:3]
	v_mfma_f32_16x16x32_bf16 v[52:55], v[148:151], v[164:167], v[52:55]
	v_mfma_f32_16x16x32_bf16 v[44:47], v[156:159], v[164:167], v[44:47]
	v_mfma_f32_16x16x32_bf16 v[36:39], v[148:151], v[172:175], v[36:39]
	v_mfma_f32_16x16x32_bf16 v[28:31], v[156:159], v[172:175], v[28:31]
	v_mfma_f32_16x16x32_bf16 v[20:23], v[148:151], v[180:183], v[20:23]
	v_mfma_f32_16x16x32_bf16 v[12:15], v[156:159], v[180:183], v[12:15]
	v_mfma_f32_16x16x32_bf16 v[4:7], v[148:151], v[188:191], v[4:7]
	v_mfma_f32_16x16x32_bf16 v[0:3], v[156:159], v[188:191], v[0:3]
	s_barrier
	s_setprio 0
	s_add_i32 s94, 0, 0x18000
	s_add_i32 s95, 0, 0x1c000
	s_add_u32 s64, s64, 0x40000
	s_addc_u32 s65, s65, 0
	s_mov_b32 m0, s71
	v_lshl_add_u64 v[200:201], s[64:65], 0, v[206:207]
	global_load_lds_dwordx4 v[200:201], off
	v_lshl_add_u64 v[200:201], s[64:65], 0, v[210:211]
	s_mov_b32 m0, s72
	s_nop 0
	global_load_lds_dwordx4 v[200:201], off
	v_add_u32_e32 v140, s94, v234
	v_add_u32_e32 v156, s95, v234
	ds_read_b128 v[128:131], v140
	ds_read_b128 v[132:135], v140 offset:1024
	ds_read_b128 v[136:139], v140 offset:2048
	ds_read_b128 v[140:143], v140 offset:3072
	ds_read_b128 v[144:147], v156
	ds_read_b128 v[148:151], v156 offset:1024
	ds_read_b128 v[152:155], v156 offset:2048
	ds_read_b128 v[156:159], v156 offset:3072
	ds_read_b128 v[160:163], v237 offset:32768
	ds_read_b128 v[164:167], v237 offset:33792
	ds_read_b128 v[168:171], v237 offset:34816
	ds_read_b128 v[172:175], v237 offset:35840
	ds_read_b128 v[176:179], v237 offset:36864
	ds_read_b128 v[180:183], v237 offset:37888
	ds_read_b128 v[184:187], v237 offset:38912
	ds_read_b128 v[188:191], v237 offset:39936
	s_waitcnt vmcnt(8)
	s_waitcnt lgkmcnt(0)
	s_setprio 1
	s_barrier
	v_mfma_f32_16x16x32_bf16 v[124:127], v[128:131], v[160:163], v[124:127]
	v_mfma_f32_16x16x32_bf16 v[120:123], v[136:139], v[160:163], v[120:123]
	v_mfma_f32_16x16x32_bf16 v[116:119], v[128:131], v[168:171], v[116:119]
	v_mfma_f32_16x16x32_bf16 v[112:115], v[136:139], v[168:171], v[112:115]
	v_mfma_f32_16x16x32_bf16 v[108:111], v[128:131], v[176:179], v[108:111]
	v_mfma_f32_16x16x32_bf16 v[100:103], v[136:139], v[176:179], v[100:103]
	v_mfma_f32_16x16x32_bf16 v[92:95], v[128:131], v[184:187], v[92:95]
	v_mfma_f32_16x16x32_bf16 v[80:83], v[136:139], v[184:187], v[80:83]
	v_mfma_f32_16x16x32_bf16 v[124:127], v[132:135], v[164:167], v[124:127]
	v_mfma_f32_16x16x32_bf16 v[120:123], v[140:143], v[164:167], v[120:123]
	v_mfma_f32_16x16x32_bf16 v[116:119], v[132:135], v[172:175], v[116:119]
	v_mfma_f32_16x16x32_bf16 v[112:115], v[140:143], v[172:175], v[112:115]
	v_mfma_f32_16x16x32_bf16 v[108:111], v[132:135], v[180:183], v[108:111]
	v_mfma_f32_16x16x32_bf16 v[100:103], v[140:143], v[180:183], v[100:103]
	v_mfma_f32_16x16x32_bf16 v[92:95], v[132:135], v[188:191], v[92:95]
	v_mfma_f32_16x16x32_bf16 v[80:83], v[140:143], v[188:191], v[80:83]
	s_setprio 0
	s_setprio 1
	v_mfma_f32_16x16x32_bf16 v[104:107], v[144:147], v[160:163], v[104:107]
	v_mfma_f32_16x16x32_bf16 v[96:99], v[152:155], v[160:163], v[96:99]
	v_mfma_f32_16x16x32_bf16 v[88:91], v[144:147], v[168:171], v[88:91]
	v_mfma_f32_16x16x32_bf16 v[84:87], v[152:155], v[168:171], v[84:87]
	v_mfma_f32_16x16x32_bf16 v[76:79], v[144:147], v[176:179], v[76:79]
	v_mfma_f32_16x16x32_bf16 v[72:75], v[152:155], v[176:179], v[72:75]
	v_mfma_f32_16x16x32_bf16 v[68:71], v[144:147], v[184:187], v[68:71]
	v_mfma_f32_16x16x32_bf16 v[64:67], v[152:155], v[184:187], v[64:67]
	v_mfma_f32_16x16x32_bf16 v[104:107], v[148:151], v[164:167], v[104:107]
	v_mfma_f32_16x16x32_bf16 v[96:99], v[156:159], v[164:167], v[96:99]
	v_mfma_f32_16x16x32_bf16 v[88:91], v[148:151], v[172:175], v[88:91]
	v_mfma_f32_16x16x32_bf16 v[84:87], v[156:159], v[172:175], v[84:87]
	v_mfma_f32_16x16x32_bf16 v[76:79], v[148:151], v[180:183], v[76:79]
	v_mfma_f32_16x16x32_bf16 v[72:75], v[156:159], v[180:183], v[72:75]
	v_mfma_f32_16x16x32_bf16 v[68:71], v[148:151], v[188:191], v[68:71]
	v_mfma_f32_16x16x32_bf16 v[64:67], v[156:159], v[188:191], v[64:67]
	s_barrier
	s_setprio 0
	s_add_i32 s64, s94, s68
	v_lshl_add_u64 v[192:193], v[192:193], 0, s[14:15]
	s_mov_b32 m0, s64
	s_nop 0
	global_load_lds_dwordx4 v[192:193], off
	s_add_i32 m0, s64, 0x2000
	s_add_u32 s62, s62, 0x40080
	v_lshl_add_u64 v[192:193], v[194:195], 0, s[14:15]
	s_addc_u32 s63, s63, 0
	s_add_i32 s64, s95, s68
	global_load_lds_dwordx4 v[192:193], off
	v_lshl_add_u64 v[192:193], s[62:63], 0, v[208:209]
	s_mov_b32 m0, s64
	s_nop 0
	global_load_lds_dwordx4 v[192:193], off
	v_lshl_add_u64 v[192:193], s[62:63], 0, v[212:213]
	s_add_i32 m0, s64, 0x2000
	s_nop 0
	global_load_lds_dwordx4 v[192:193], off
	v_lshl_add_u64 v[192:193], v[196:197], 0, s[14:15]
	s_mov_b32 m0, s76
	s_nop 0
	global_load_lds_dwordx4 v[192:193], off
	v_lshl_add_u64 v[192:193], v[198:199], 0, s[14:15]
	s_mov_b32 m0, s77
	s_nop 0
	global_load_lds_dwordx4 v[192:193], off
	ds_read_b128 v[160:163], v237 offset:49152
	ds_read_b128 v[164:167], v237 offset:50176
	ds_read_b128 v[168:171], v237 offset:51200
	ds_read_b128 v[172:175], v237 offset:52224
	ds_read_b128 v[176:179], v237 offset:53248
	ds_read_b128 v[180:183], v237 offset:54272
	ds_read_b128 v[184:187], v237 offset:55296
	ds_read_b128 v[188:191], v237 offset:56320
	s_waitcnt vmcnt(8)
	s_waitcnt lgkmcnt(0)
	s_setprio 1
	s_barrier
	v_mfma_f32_16x16x32_bf16 v[60:63], v[128:131], v[160:163], v[60:63]
	v_mfma_f32_16x16x32_bf16 v[56:59], v[136:139], v[160:163], v[56:59]
	v_mfma_f32_16x16x32_bf16 v[48:51], v[128:131], v[168:171], v[48:51]
	v_mfma_f32_16x16x32_bf16 v[40:43], v[136:139], v[168:171], v[40:43]
	v_mfma_f32_16x16x32_bf16 v[32:35], v[128:131], v[176:179], v[32:35]
	v_mfma_f32_16x16x32_bf16 v[24:27], v[136:139], v[176:179], v[24:27]
	v_mfma_f32_16x16x32_bf16 v[16:19], v[128:131], v[184:187], v[16:19]
	v_mfma_f32_16x16x32_bf16 v[8:11], v[136:139], v[184:187], v[8:11]
	v_mfma_f32_16x16x32_bf16 v[60:63], v[132:135], v[164:167], v[60:63]
	v_mfma_f32_16x16x32_bf16 v[56:59], v[140:143], v[164:167], v[56:59]
	v_mfma_f32_16x16x32_bf16 v[48:51], v[132:135], v[172:175], v[48:51]
	v_mfma_f32_16x16x32_bf16 v[40:43], v[140:143], v[172:175], v[40:43]
	v_mfma_f32_16x16x32_bf16 v[32:35], v[132:135], v[180:183], v[32:35]
	v_mfma_f32_16x16x32_bf16 v[24:27], v[140:143], v[180:183], v[24:27]
	v_mfma_f32_16x16x32_bf16 v[16:19], v[132:135], v[188:191], v[16:19]
	v_mfma_f32_16x16x32_bf16 v[8:11], v[140:143], v[188:191], v[8:11]
	s_setprio 0
	s_setprio 1
	v_mfma_f32_16x16x32_bf16 v[52:55], v[144:147], v[160:163], v[52:55]
	v_mfma_f32_16x16x32_bf16 v[44:47], v[152:155], v[160:163], v[44:47]
	v_mfma_f32_16x16x32_bf16 v[36:39], v[144:147], v[168:171], v[36:39]
	v_mfma_f32_16x16x32_bf16 v[28:31], v[152:155], v[168:171], v[28:31]
	v_mfma_f32_16x16x32_bf16 v[20:23], v[144:147], v[176:179], v[20:23]
	v_mfma_f32_16x16x32_bf16 v[12:15], v[152:155], v[176:179], v[12:15]
	v_mfma_f32_16x16x32_bf16 v[4:7], v[144:147], v[184:187], v[4:7]
	v_mfma_f32_16x16x32_bf16 v[0:3], v[152:155], v[184:187], v[0:3]
	v_mfma_f32_16x16x32_bf16 v[52:55], v[148:151], v[164:167], v[52:55]
	v_mfma_f32_16x16x32_bf16 v[44:47], v[156:159], v[164:167], v[44:47]
	v_mfma_f32_16x16x32_bf16 v[36:39], v[148:151], v[172:175], v[36:39]
	v_mfma_f32_16x16x32_bf16 v[28:31], v[156:159], v[172:175], v[28:31]
	v_mfma_f32_16x16x32_bf16 v[20:23], v[148:151], v[180:183], v[20:23]
	v_mfma_f32_16x16x32_bf16 v[12:15], v[156:159], v[180:183], v[12:15]
	v_mfma_f32_16x16x32_bf16 v[4:7], v[148:151], v[188:191], v[4:7]
	v_mfma_f32_16x16x32_bf16 v[0:3], v[156:159], v[188:191], v[0:3]
	s_barrier
	s_setprio 0
	s_add_i32 s93, s93, 2
	s_add_u32 s48, s48, 0x100
	s_addc_u32 s49, s49, 0
	s_add_u32 s60, s60, 0x100
	s_addc_u32 s61, s61, 0
	s_cmp_gt_u32 s93, 13
	s_cbranch_scc0 .LBB0_723
	s_and_b64 vcc, exec, s[16:17]
	s_cbranch_vccz .LBB0_726
	s_barrier

.LBB0_1109:
	s_add_u32 s30, s28, 0xfffc0080
	s_addc_u32 s31, s29, -1
	s_cmp_eq_u32 s64, 12
	s_cselect_b32 s35, s19, s31
	s_cselect_b32 s34, s25, s30
	s_cselect_b32 s31, s17, s63
	s_cselect_b32 s30, s61, s62
	v_lshl_add_u64 v[206:207], s[28:29], 0, v[200:201]
	s_add_i32 m0, s27, 0xc000
	s_nop 0
	global_load_lds_dwordx4 v[206:207], off
	v_lshl_add_u64 v[206:207], s[28:29], 0, v[202:203]
	s_add_i32 m0, s27, 0xe000
	s_nop 0
	global_load_lds_dwordx4 v[206:207], off
	ds_read_b128 v[120:123], v246
	ds_read_b128 v[124:127], v246 offset:1024
	ds_read_b128 v[128:131], v246 offset:2048
	ds_read_b128 v[132:135], v246 offset:3072
	ds_read_b128 v[140:143], v247
	ds_read_b128 v[148:151], v247 offset:1024
	ds_read_b128 v[152:155], v247 offset:2048
	ds_read_b128 v[156:159], v247 offset:3072
	ds_read_b128 v[160:163], v248
	ds_read_b128 v[164:167], v248 offset:1024
	ds_read_b128 v[168:171], v248 offset:2048
	ds_read_b128 v[172:175], v248 offset:3072
	ds_read_b128 v[176:179], v248 offset:4096
	ds_read_b128 v[180:183], v248 offset:5120
	ds_read_b128 v[184:187], v248 offset:6144
	ds_read_b128 v[188:191], v248 offset:7168
	s_nop 0
	s_waitcnt vmcnt(8)
	s_waitcnt lgkmcnt(0)
	s_setprio 1
	s_barrier
	v_mfma_f32_16x16x32_bf16 v[144:147], v[120:123], v[160:163], v[144:147]
	v_mfma_f32_16x16x32_bf16 v[136:139], v[128:131], v[160:163], v[136:139]
	v_mfma_f32_16x16x32_bf16 v[108:111], v[120:123], v[168:171], v[108:111]
	v_mfma_f32_16x16x32_bf16 v[104:107], v[128:131], v[168:171], v[104:107]
	v_mfma_f32_16x16x32_bf16 v[92:95], v[120:123], v[176:179], v[92:95]
	v_mfma_f32_16x16x32_bf16 v[88:91], v[128:131], v[176:179], v[88:91]
	v_mfma_f32_16x16x32_bf16 v[76:79], v[120:123], v[184:187], v[76:79]
	v_mfma_f32_16x16x32_bf16 v[72:75], v[128:131], v[184:187], v[72:75]
	v_mfma_f32_16x16x32_bf16 v[144:147], v[124:127], v[164:167], v[144:147]
	v_mfma_f32_16x16x32_bf16 v[136:139], v[132:135], v[164:167], v[136:139]
	v_mfma_f32_16x16x32_bf16 v[108:111], v[124:127], v[172:175], v[108:111]
	v_mfma_f32_16x16x32_bf16 v[104:107], v[132:135], v[172:175], v[104:107]
	v_mfma_f32_16x16x32_bf16 v[92:95], v[124:127], v[180:183], v[92:95]
	v_mfma_f32_16x16x32_bf16 v[88:91], v[132:135], v[180:183], v[88:91]
	v_mfma_f32_16x16x32_bf16 v[76:79], v[124:127], v[188:191], v[76:79]
	v_mfma_f32_16x16x32_bf16 v[72:75], v[132:135], v[188:191], v[72:75]
	s_setprio 0
	s_setprio 1
	v_mfma_f32_16x16x32_bf16 v[116:119], v[140:143], v[160:163], v[116:119]
	v_mfma_f32_16x16x32_bf16 v[112:115], v[152:155], v[160:163], v[112:115]
	v_mfma_f32_16x16x32_bf16 v[100:103], v[140:143], v[168:171], v[100:103]
	v_mfma_f32_16x16x32_bf16 v[96:99], v[152:155], v[168:171], v[96:99]
	v_mfma_f32_16x16x32_bf16 v[84:87], v[140:143], v[176:179], v[84:87]
	v_mfma_f32_16x16x32_bf16 v[80:83], v[152:155], v[176:179], v[80:83]
	v_mfma_f32_16x16x32_bf16 v[68:71], v[140:143], v[184:187], v[68:71]
	v_mfma_f32_16x16x32_bf16 v[64:67], v[152:155], v[184:187], v[64:67]
	v_mfma_f32_16x16x32_bf16 v[116:119], v[148:151], v[164:167], v[116:119]
	v_mfma_f32_16x16x32_bf16 v[112:115], v[156:159], v[164:167], v[112:115]
	v_mfma_f32_16x16x32_bf16 v[100:103], v[148:151], v[172:175], v[100:103]
	v_mfma_f32_16x16x32_bf16 v[96:99], v[156:159], v[172:175], v[96:99]
	v_mfma_f32_16x16x32_bf16 v[84:87], v[148:151], v[180:183], v[84:87]
	v_mfma_f32_16x16x32_bf16 v[80:83], v[156:159], v[180:183], v[80:83]
	v_mfma_f32_16x16x32_bf16 v[68:71], v[148:151], v[188:191], v[68:71]
	v_mfma_f32_16x16x32_bf16 v[64:67], v[156:159], v[188:191], v[64:67]
	s_barrier
	s_setprio 0
	s_add_i32 s65, s51, s37
	v_lshl_add_u64 v[206:207], s[30:31], 0, v[194:195]
	s_mov_b32 m0, s65
	s_nop 0
	global_load_lds_dwordx4 v[206:207], off
	s_add_i32 m0, s65, 0x2000
	s_add_u32 s66, s30, 0x40000
	v_lshl_add_u64 v[208:209], s[30:31], 0, v[198:199]
	s_addc_u32 s67, s31, 0
	s_add_i32 s65, s60, s37
	global_load_lds_dwordx4 v[208:209], off
	v_lshl_add_u64 v[210:211], s[66:67], 0, v[194:195]
	s_mov_b32 m0, s65
	v_lshl_add_u64 v[212:213], s[34:35], 0, v[196:197]
	global_load_lds_dwordx4 v[210:211], off
	v_lshl_add_u64 v[210:211], s[66:67], 0, v[198:199]
	s_add_i32 m0, s65, 0x2000
	s_nop 0
	global_load_lds_dwordx4 v[210:211], off
	v_lshl_add_u64 v[210:211], s[34:35], 0, v[192:193]
	s_mov_b32 m0, s27
	s_nop 0
	global_load_lds_dwordx4 v[210:211], off
	s_mov_b32 m0, s38
	s_nop 0
	global_load_lds_dwordx4 v[212:213], off
	ds_read_b128 v[160:163], v248 offset:16384
	ds_read_b128 v[164:167], v248 offset:17408
	ds_read_b128 v[168:171], v248 offset:18432
	ds_read_b128 v[172:175], v248 offset:19456
	ds_read_b128 v[176:179], v248 offset:20480
	ds_read_b128 v[180:183], v248 offset:21504
	ds_read_b128 v[184:187], v248 offset:22528
	ds_read_b128 v[188:191], v248 offset:23552
	s_nop 0
	s_waitcnt vmcnt(8)
	s_waitcnt lgkmcnt(0)
	s_setprio 1
	s_barrier
	v_mfma_f32_16x16x32_bf16 v[60:63], v[120:123], v[160:163], v[60:63]
	v_mfma_f32_16x16x32_bf16 v[56:59], v[128:131], v[160:163], v[56:59]
	v_mfma_f32_16x16x32_bf16 v[44:47], v[120:123], v[168:171], v[44:47]
	v_mfma_f32_16x16x32_bf16 v[40:43], v[128:131], v[168:171], v[40:43]
	v_mfma_f32_16x16x32_bf16 v[28:31], v[120:123], v[176:179], v[28:31]
	v_mfma_f32_16x16x32_bf16 v[24:27], v[128:131], v[176:179], v[24:27]
	v_mfma_f32_16x16x32_bf16 v[12:15], v[120:123], v[184:187], v[12:15]
	v_mfma_f32_16x16x32_bf16 v[8:11], v[128:131], v[184:187], v[8:11]
	v_mfma_f32_16x16x32_bf16 v[60:63], v[124:127], v[164:167], v[60:63]
	v_mfma_f32_16x16x32_bf16 v[56:59], v[132:135], v[164:167], v[56:59]
	v_mfma_f32_16x16x32_bf16 v[44:47], v[124:127], v[172:175], v[44:47]
	v_mfma_f32_16x16x32_bf16 v[40:43], v[132:135], v[172:175], v[40:43]
	v_mfma_f32_16x16x32_bf16 v[28:31], v[124:127], v[180:183], v[28:31]
	v_mfma_f32_16x16x32_bf16 v[24:27], v[132:135], v[180:183], v[24:27]
	v_mfma_f32_16x16x32_bf16 v[12:15], v[124:127], v[188:191], v[12:15]
	v_mfma_f32_16x16x32_bf16 v[8:11], v[132:135], v[188:191], v[8:11]
	s_setprio 0
	s_setprio 1
	v_mfma_f32_16x16x32_bf16 v[52:55], v[140:143], v[160:163], v[52:55]
	v_mfma_f32_16x16x32_bf16 v[48:51], v[152:155], v[160:163], v[48:51]
	v_mfma_f32_16x16x32_bf16 v[36:39], v[140:143], v[168:171], v[36:39]
	v_mfma_f32_16x16x32_bf16 v[32:35], v[152:155], v[168:171], v[32:35]
	v_mfma_f32_16x16x32_bf16 v[20:23], v[140:143], v[176:179], v[20:23]
	v_mfma_f32_16x16x32_bf16 v[16:19], v[152:155], v[176:179], v[16:19]
	v_mfma_f32_16x16x32_bf16 v[4:7], v[140:143], v[184:187], v[4:7]
	v_mfma_f32_16x16x32_bf16 v[0:3], v[152:155], v[184:187], v[0:3]
	v_mfma_f32_16x16x32_bf16 v[52:55], v[148:151], v[164:167], v[52:55]
	v_mfma_f32_16x16x32_bf16 v[48:51], v[156:159], v[164:167], v[48:51]
	v_mfma_f32_16x16x32_bf16 v[36:39], v[148:151], v[172:175], v[36:39]
	v_mfma_f32_16x16x32_bf16 v[32:35], v[156:159], v[172:175], v[32:35]
	v_mfma_f32_16x16x32_bf16 v[20:23], v[148:151], v[180:183], v[20:23]
	v_mfma_f32_16x16x32_bf16 v[16:19], v[156:159], v[180:183], v[16:19]
	v_mfma_f32_16x16x32_bf16 v[4:7], v[148:151], v[188:191], v[4:7]
	v_mfma_f32_16x16x32_bf16 v[0:3], v[156:159], v[188:191], v[0:3]
	s_barrier
	s_setprio 0
	s_add_i32 s65, 0, 0x18000
	s_add_i32 s66, 0, 0x1c000
	s_add_u32 s34, s34, 0x40000
	s_addc_u32 s35, s35, 0
	s_mov_b32 m0, s39
	v_lshl_add_u64 v[214:215], s[34:35], 0, v[192:193]
	global_load_lds_dwordx4 v[214:215], off
	v_lshl_add_u64 v[214:215], s[34:35], 0, v[196:197]
	s_mov_b32 m0, s40
	s_nop 0
	global_load_lds_dwordx4 v[214:215], off
	v_add_u32_e32 v132, s65, v245
	v_add_u32_e32 v156, s66, v245
	ds_read_b128 v[120:123], v132
	ds_read_b128 v[124:127], v132 offset:1024
	ds_read_b128 v[128:131], v132 offset:2048
	ds_read_b128 v[132:135], v132 offset:3072
	ds_read_b128 v[140:143], v156
	ds_read_b128 v[148:151], v156 offset:1024
	ds_read_b128 v[152:155], v156 offset:2048
	ds_read_b128 v[156:159], v156 offset:3072
	ds_read_b128 v[160:163], v248 offset:32768
	ds_read_b128 v[164:167], v248 offset:33792
	ds_read_b128 v[168:171], v248 offset:34816
	ds_read_b128 v[172:175], v248 offset:35840
	ds_read_b128 v[176:179], v248 offset:36864
	ds_read_b128 v[180:183], v248 offset:37888
	ds_read_b128 v[184:187], v248 offset:38912
	ds_read_b128 v[188:191], v248 offset:39936
	s_waitcnt vmcnt(8)
	s_waitcnt lgkmcnt(0)
	s_setprio 1
	s_barrier
	v_mfma_f32_16x16x32_bf16 v[144:147], v[120:123], v[160:163], v[144:147]
	v_mfma_f32_16x16x32_bf16 v[136:139], v[128:131], v[160:163], v[136:139]
	v_mfma_f32_16x16x32_bf16 v[108:111], v[120:123], v[168:171], v[108:111]
	v_mfma_f32_16x16x32_bf16 v[104:107], v[128:131], v[168:171], v[104:107]
	v_mfma_f32_16x16x32_bf16 v[92:95], v[120:123], v[176:179], v[92:95]
	v_mfma_f32_16x16x32_bf16 v[88:91], v[128:131], v[176:179], v[88:91]
	v_mfma_f32_16x16x32_bf16 v[76:79], v[120:123], v[184:187], v[76:79]
	v_mfma_f32_16x16x32_bf16 v[72:75], v[128:131], v[184:187], v[72:75]
	v_mfma_f32_16x16x32_bf16 v[144:147], v[124:127], v[164:167], v[144:147]
	v_mfma_f32_16x16x32_bf16 v[136:139], v[132:135], v[164:167], v[136:139]
	v_mfma_f32_16x16x32_bf16 v[108:111], v[124:127], v[172:175], v[108:111]
	v_mfma_f32_16x16x32_bf16 v[104:107], v[132:135], v[172:175], v[104:107]
	v_mfma_f32_16x16x32_bf16 v[92:95], v[124:127], v[180:183], v[92:95]
	v_mfma_f32_16x16x32_bf16 v[88:91], v[132:135], v[180:183], v[88:91]
	v_mfma_f32_16x16x32_bf16 v[76:79], v[124:127], v[188:191], v[76:79]
	v_mfma_f32_16x16x32_bf16 v[72:75], v[132:135], v[188:191], v[72:75]
	s_setprio 0
	s_setprio 1
	v_mfma_f32_16x16x32_bf16 v[116:119], v[140:143], v[160:163], v[116:119]
	v_mfma_f32_16x16x32_bf16 v[112:115], v[152:155], v[160:163], v[112:115]
	v_mfma_f32_16x16x32_bf16 v[100:103], v[140:143], v[168:171], v[100:103]
	v_mfma_f32_16x16x32_bf16 v[96:99], v[152:155], v[168:171], v[96:99]
	v_mfma_f32_16x16x32_bf16 v[84:87], v[140:143], v[176:179], v[84:87]
	v_mfma_f32_16x16x32_bf16 v[80:83], v[152:155], v[176:179], v[80:83]
	v_mfma_f32_16x16x32_bf16 v[68:71], v[140:143], v[184:187], v[68:71]
	v_mfma_f32_16x16x32_bf16 v[64:67], v[152:155], v[184:187], v[64:67]
	v_mfma_f32_16x16x32_bf16 v[116:119], v[148:151], v[164:167], v[116:119]
	v_mfma_f32_16x16x32_bf16 v[112:115], v[156:159], v[164:167], v[112:115]
	v_mfma_f32_16x16x32_bf16 v[100:103], v[148:151], v[172:175], v[100:103]
	v_mfma_f32_16x16x32_bf16 v[96:99], v[156:159], v[172:175], v[96:99]
	v_mfma_f32_16x16x32_bf16 v[84:87], v[148:151], v[180:183], v[84:87]
	v_mfma_f32_16x16x32_bf16 v[80:83], v[156:159], v[180:183], v[80:83]
	v_mfma_f32_16x16x32_bf16 v[68:71], v[148:151], v[188:191], v[68:71]
	v_mfma_f32_16x16x32_bf16 v[64:67], v[156:159], v[188:191], v[64:67]
	s_barrier
	s_setprio 0
	s_add_i32 s34, s65, s37
	v_lshl_add_u64 v[206:207], v[206:207], 0, s[12:13]
	s_mov_b32 m0, s34
	s_nop 0
	global_load_lds_dwordx4 v[206:207], off
	s_add_i32 m0, s34, 0x2000
	s_add_u32 s30, s30, 0x40080
	v_lshl_add_u64 v[206:207], v[208:209], 0, s[12:13]
	s_addc_u32 s31, s31, 0
	s_add_i32 s34, s66, s37
	global_load_lds_dwordx4 v[206:207], off
	v_lshl_add_u64 v[206:207], s[30:31], 0, v[194:195]
	s_mov_b32 m0, s34
	s_nop 0
	global_load_lds_dwordx4 v[206:207], off
	v_lshl_add_u64 v[206:207], s[30:31], 0, v[198:199]
	s_add_i32 m0, s34, 0x2000
	s_nop 0
	global_load_lds_dwordx4 v[206:207], off
	v_lshl_add_u64 v[206:207], v[210:211], 0, s[12:13]
	s_mov_b32 m0, s46
	s_nop 0
	global_load_lds_dwordx4 v[206:207], off
	v_lshl_add_u64 v[206:207], v[212:213], 0, s[12:13]
	s_mov_b32 m0, s47
	s_nop 0
	global_load_lds_dwordx4 v[206:207], off
	ds_read_b128 v[160:163], v248 offset:49152
	ds_read_b128 v[164:167], v248 offset:50176
	ds_read_b128 v[168:171], v248 offset:51200
	ds_read_b128 v[172:175], v248 offset:52224
	ds_read_b128 v[176:179], v248 offset:53248
	ds_read_b128 v[180:183], v248 offset:54272
	ds_read_b128 v[184:187], v248 offset:55296
	ds_read_b128 v[188:191], v248 offset:56320
	s_waitcnt vmcnt(8)
	s_waitcnt lgkmcnt(0)
	s_setprio 1
	s_barrier
	v_mfma_f32_16x16x32_bf16 v[60:63], v[120:123], v[160:163], v[60:63]
	v_mfma_f32_16x16x32_bf16 v[56:59], v[128:131], v[160:163], v[56:59]
	v_mfma_f32_16x16x32_bf16 v[44:47], v[120:123], v[168:171], v[44:47]
	v_mfma_f32_16x16x32_bf16 v[40:43], v[128:131], v[168:171], v[40:43]
	v_mfma_f32_16x16x32_bf16 v[28:31], v[120:123], v[176:179], v[28:31]
	v_mfma_f32_16x16x32_bf16 v[24:27], v[128:131], v[176:179], v[24:27]
	v_mfma_f32_16x16x32_bf16 v[12:15], v[120:123], v[184:187], v[12:15]
	v_mfma_f32_16x16x32_bf16 v[8:11], v[128:131], v[184:187], v[8:11]
	v_mfma_f32_16x16x32_bf16 v[60:63], v[124:127], v[164:167], v[60:63]
	v_mfma_f32_16x16x32_bf16 v[56:59], v[132:135], v[164:167], v[56:59]
	v_mfma_f32_16x16x32_bf16 v[44:47], v[124:127], v[172:175], v[44:47]
	v_mfma_f32_16x16x32_bf16 v[40:43], v[132:135], v[172:175], v[40:43]
	v_mfma_f32_16x16x32_bf16 v[28:31], v[124:127], v[180:183], v[28:31]
	v_mfma_f32_16x16x32_bf16 v[24:27], v[132:135], v[180:183], v[24:27]
	v_mfma_f32_16x16x32_bf16 v[12:15], v[124:127], v[188:191], v[12:15]
	v_mfma_f32_16x16x32_bf16 v[8:11], v[132:135], v[188:191], v[8:11]
	s_setprio 0
	s_setprio 1
	v_mfma_f32_16x16x32_bf16 v[52:55], v[140:143], v[160:163], v[52:55]
	v_mfma_f32_16x16x32_bf16 v[48:51], v[152:155], v[160:163], v[48:51]
	v_mfma_f32_16x16x32_bf16 v[36:39], v[140:143], v[168:171], v[36:39]
	v_mfma_f32_16x16x32_bf16 v[32:35], v[152:155], v[168:171], v[32:35]
	v_mfma_f32_16x16x32_bf16 v[20:23], v[140:143], v[176:179], v[20:23]
	v_mfma_f32_16x16x32_bf16 v[16:19], v[152:155], v[176:179], v[16:19]
	v_mfma_f32_16x16x32_bf16 v[4:7], v[140:143], v[184:187], v[4:7]
	v_mfma_f32_16x16x32_bf16 v[0:3], v[152:155], v[184:187], v[0:3]
	v_mfma_f32_16x16x32_bf16 v[52:55], v[148:151], v[164:167], v[52:55]
	v_mfma_f32_16x16x32_bf16 v[48:51], v[156:159], v[164:167], v[48:51]
	v_mfma_f32_16x16x32_bf16 v[36:39], v[148:151], v[172:175], v[36:39]
	v_mfma_f32_16x16x32_bf16 v[32:35], v[156:159], v[172:175], v[32:35]
	v_mfma_f32_16x16x32_bf16 v[20:23], v[148:151], v[180:183], v[20:23]
	v_mfma_f32_16x16x32_bf16 v[16:19], v[156:159], v[180:183], v[16:19]
	v_mfma_f32_16x16x32_bf16 v[4:7], v[148:151], v[188:191], v[4:7]
	v_mfma_f32_16x16x32_bf16 v[0:3], v[156:159], v[188:191], v[0:3]
	s_barrier
	s_setprio 0
	s_add_i32 s64, s64, 2
	s_add_u32 s28, s28, 0x100
	s_addc_u32 s29, s29, 0
	s_add_u32 s62, s62, 0x100
	s_addc_u32 s63, s63, 0
	s_cmp_gt_u32 s64, 13
	s_cbranch_scc0 .LBB0_1109
	s_and_b64 vcc, exec, s[14:15]
	s_cbranch_vccz .LBB0_1112
	s_barrier

.LBB0_1193:
	s_add_u32 s30, s28, 0xfffc0080
	s_addc_u32 s31, s29, -1
	s_cmp_eq_u32 s62, 12
	s_cselect_b32 s35, s19, s31
	s_cselect_b32 s34, s50, s30
	s_cselect_b32 s31, s17, s61
	s_cselect_b32 s30, s51, s60
	v_lshl_add_u64 v[144:145], s[28:29], 0, v[136:137]
	s_add_i32 m0, s25, 0xc000
	s_nop 0
	global_load_lds_dwordx4 v[144:145], off
	v_lshl_add_u64 v[144:145], s[28:29], 0, v[138:139]
	s_add_i32 m0, s25, 0xe000
	s_nop 0
	global_load_lds_dwordx4 v[144:145], off
	ds_read_b128 v[154:157], v149
	ds_read_b128 v[158:161], v149 offset:1024
	ds_read_b128 v[162:165], v149 offset:2048
	ds_read_b128 v[166:169], v149 offset:3072
	ds_read_b128 v[170:173], v150
	ds_read_b128 v[174:177], v150 offset:1024
	ds_read_b128 v[178:181], v150 offset:2048
	ds_read_b128 v[182:185], v150 offset:3072
	ds_read_b128 v[186:189], v151
	ds_read_b128 v[190:193], v151 offset:1024
	ds_read_b128 v[194:197], v151 offset:2048
	ds_read_b128 v[198:201], v151 offset:3072
	ds_read_b128 v[202:205], v151 offset:4096
	ds_read_b128 v[206:209], v151 offset:5120
	ds_read_b128 v[210:213], v151 offset:6144
	ds_read_b128 v[214:217], v151 offset:7168
	s_waitcnt vmcnt(8)
	s_waitcnt lgkmcnt(0)
	s_setprio 1
	s_barrier
	v_mfma_f32_16x16x32_bf16 v[116:119], v[154:157], v[186:189], v[116:119]
	v_mfma_f32_16x16x32_bf16 v[112:115], v[162:165], v[186:189], v[112:115]
	v_mfma_f32_16x16x32_bf16 v[108:111], v[154:157], v[194:197], v[108:111]
	v_mfma_f32_16x16x32_bf16 v[100:103], v[162:165], v[194:197], v[100:103]
	v_mfma_f32_16x16x32_bf16 v[92:95], v[154:157], v[202:205], v[92:95]
	v_mfma_f32_16x16x32_bf16 v[84:87], v[162:165], v[202:205], v[84:87]
	v_mfma_f32_16x16x32_bf16 v[76:79], v[154:157], v[210:213], v[76:79]
	v_mfma_f32_16x16x32_bf16 v[68:71], v[162:165], v[210:213], v[68:71]
	v_mfma_f32_16x16x32_bf16 v[116:119], v[158:161], v[190:193], v[116:119]
	v_mfma_f32_16x16x32_bf16 v[112:115], v[166:169], v[190:193], v[112:115]
	v_mfma_f32_16x16x32_bf16 v[108:111], v[158:161], v[198:201], v[108:111]
	v_mfma_f32_16x16x32_bf16 v[100:103], v[166:169], v[198:201], v[100:103]
	v_mfma_f32_16x16x32_bf16 v[92:95], v[158:161], v[206:209], v[92:95]
	v_mfma_f32_16x16x32_bf16 v[84:87], v[166:169], v[206:209], v[84:87]
	v_mfma_f32_16x16x32_bf16 v[76:79], v[158:161], v[214:217], v[76:79]
	v_mfma_f32_16x16x32_bf16 v[68:71], v[166:169], v[214:217], v[68:71]
	s_setprio 0
	s_setprio 1
	v_mfma_f32_16x16x32_bf16 v[124:127], v[170:173], v[186:189], v[124:127]
	v_mfma_f32_16x16x32_bf16 v[120:123], v[178:181], v[186:189], v[120:123]
	v_mfma_f32_16x16x32_bf16 v[104:107], v[170:173], v[194:197], v[104:107]
	v_mfma_f32_16x16x32_bf16 v[96:99], v[178:181], v[194:197], v[96:99]
	v_mfma_f32_16x16x32_bf16 v[88:91], v[170:173], v[202:205], v[88:91]
	v_mfma_f32_16x16x32_bf16 v[80:83], v[178:181], v[202:205], v[80:83]
	v_mfma_f32_16x16x32_bf16 v[72:75], v[170:173], v[210:213], v[72:75]
	v_mfma_f32_16x16x32_bf16 v[64:67], v[178:181], v[210:213], v[64:67]
	v_mfma_f32_16x16x32_bf16 v[124:127], v[174:177], v[190:193], v[124:127]
	v_mfma_f32_16x16x32_bf16 v[120:123], v[182:185], v[190:193], v[120:123]
	v_mfma_f32_16x16x32_bf16 v[104:107], v[174:177], v[198:201], v[104:107]
	v_mfma_f32_16x16x32_bf16 v[96:99], v[182:185], v[198:201], v[96:99]
	v_mfma_f32_16x16x32_bf16 v[88:91], v[174:177], v[206:209], v[88:91]
	v_mfma_f32_16x16x32_bf16 v[80:83], v[182:185], v[206:209], v[80:83]
	v_mfma_f32_16x16x32_bf16 v[72:75], v[174:177], v[214:217], v[72:75]
	v_mfma_f32_16x16x32_bf16 v[64:67], v[182:185], v[214:217], v[64:67]
	s_barrier
	s_setprio 0
	s_add_i32 s63, s47, s5
	v_lshl_add_u64 v[144:145], s[30:31], 0, v[132:133]
	s_mov_b32 m0, s63
	s_nop 0
	global_load_lds_dwordx4 v[144:145], off
	s_add_i32 m0, s63, 0x2000
	s_add_u32 s64, s30, 0x40000
	v_lshl_add_u64 v[218:219], s[30:31], 0, v[128:129]
	s_addc_u32 s65, s31, 0
	s_add_i32 s63, s48, s5
	global_load_lds_dwordx4 v[218:219], off
	v_lshl_add_u64 v[220:221], s[64:65], 0, v[132:133]
	s_mov_b32 m0, s63
	v_lshl_add_u64 v[222:223], s[34:35], 0, v[130:131]
	global_load_lds_dwordx4 v[220:221], off
	v_lshl_add_u64 v[220:221], s[64:65], 0, v[128:129]
	s_add_i32 m0, s63, 0x2000
	s_nop 0
	global_load_lds_dwordx4 v[220:221], off
	v_lshl_add_u64 v[220:221], s[34:35], 0, v[134:135]
	s_mov_b32 m0, s25
	s_nop 0
	global_load_lds_dwordx4 v[220:221], off
	s_mov_b32 m0, s27
	s_nop 0
	global_load_lds_dwordx4 v[222:223], off
	ds_read_b128 v[186:189], v151 offset:16384
	ds_read_b128 v[190:193], v151 offset:17408
	ds_read_b128 v[194:197], v151 offset:18432
	ds_read_b128 v[198:201], v151 offset:19456
	ds_read_b128 v[202:205], v151 offset:20480
	ds_read_b128 v[206:209], v151 offset:21504
	ds_read_b128 v[210:213], v151 offset:22528
	ds_read_b128 v[214:217], v151 offset:23552
	s_nop 0
	s_waitcnt vmcnt(8)
	s_waitcnt lgkmcnt(0)
	s_setprio 1
	s_barrier
	v_mfma_f32_16x16x32_bf16 v[60:63], v[154:157], v[186:189], v[60:63]
	v_mfma_f32_16x16x32_bf16 v[52:55], v[162:165], v[186:189], v[52:55]
	v_mfma_f32_16x16x32_bf16 v[44:47], v[154:157], v[194:197], v[44:47]
	v_mfma_f32_16x16x32_bf16 v[36:39], v[162:165], v[194:197], v[36:39]
	v_mfma_f32_16x16x32_bf16 v[28:31], v[154:157], v[202:205], v[28:31]
	v_mfma_f32_16x16x32_bf16 v[20:23], v[162:165], v[202:205], v[20:23]
	v_mfma_f32_16x16x32_bf16 v[12:15], v[154:157], v[210:213], v[12:15]
	v_mfma_f32_16x16x32_bf16 v[4:7], v[162:165], v[210:213], v[4:7]
	v_mfma_f32_16x16x32_bf16 v[60:63], v[158:161], v[190:193], v[60:63]
	v_mfma_f32_16x16x32_bf16 v[52:55], v[166:169], v[190:193], v[52:55]
	v_mfma_f32_16x16x32_bf16 v[44:47], v[158:161], v[198:201], v[44:47]
	v_mfma_f32_16x16x32_bf16 v[36:39], v[166:169], v[198:201], v[36:39]
	v_mfma_f32_16x16x32_bf16 v[28:31], v[158:161], v[206:209], v[28:31]
	v_mfma_f32_16x16x32_bf16 v[20:23], v[166:169], v[206:209], v[20:23]
	v_mfma_f32_16x16x32_bf16 v[12:15], v[158:161], v[214:217], v[12:15]
	v_mfma_f32_16x16x32_bf16 v[4:7], v[166:169], v[214:217], v[4:7]
	s_setprio 0
	s_setprio 1
	v_mfma_f32_16x16x32_bf16 v[56:59], v[170:173], v[186:189], v[56:59]
	v_mfma_f32_16x16x32_bf16 v[48:51], v[178:181], v[186:189], v[48:51]
	v_mfma_f32_16x16x32_bf16 v[40:43], v[170:173], v[194:197], v[40:43]
	v_mfma_f32_16x16x32_bf16 v[32:35], v[178:181], v[194:197], v[32:35]
	v_mfma_f32_16x16x32_bf16 v[24:27], v[170:173], v[202:205], v[24:27]
	v_mfma_f32_16x16x32_bf16 v[16:19], v[178:181], v[202:205], v[16:19]
	v_mfma_f32_16x16x32_bf16 v[8:11], v[170:173], v[210:213], v[8:11]
	v_mfma_f32_16x16x32_bf16 v[0:3], v[178:181], v[210:213], v[0:3]
	v_mfma_f32_16x16x32_bf16 v[56:59], v[174:177], v[190:193], v[56:59]
	v_mfma_f32_16x16x32_bf16 v[48:51], v[182:185], v[190:193], v[48:51]
	v_mfma_f32_16x16x32_bf16 v[40:43], v[174:177], v[198:201], v[40:43]
	v_mfma_f32_16x16x32_bf16 v[32:35], v[182:185], v[198:201], v[32:35]
	v_mfma_f32_16x16x32_bf16 v[24:27], v[174:177], v[206:209], v[24:27]
	v_mfma_f32_16x16x32_bf16 v[16:19], v[182:185], v[206:209], v[16:19]
	v_mfma_f32_16x16x32_bf16 v[8:11], v[174:177], v[214:217], v[8:11]
	v_mfma_f32_16x16x32_bf16 v[0:3], v[182:185], v[214:217], v[0:3]
	s_barrier
	s_setprio 0
	s_add_i32 s63, 0, 0x18000
	s_add_i32 s64, 0, 0x1c000
	s_add_u32 s34, s34, 0x40000
	s_addc_u32 s35, s35, 0
	s_mov_b32 m0, s38
	v_lshl_add_u64 v[224:225], s[34:35], 0, v[134:135]
	global_load_lds_dwordx4 v[224:225], off
	v_lshl_add_u64 v[224:225], s[34:35], 0, v[130:131]
	s_mov_b32 m0, s39
	s_nop 0
	global_load_lds_dwordx4 v[224:225], off
	v_add_u32_e32 v153, s63, v147
	ds_read_b128 v[154:157], v153
	ds_read_b128 v[158:161], v153 offset:1024
	ds_read_b128 v[162:165], v153 offset:2048
	ds_read_b128 v[166:169], v153 offset:3072
	v_add_u32_e32 v153, s64, v147
	ds_read_b128 v[170:173], v153
	ds_read_b128 v[174:177], v153 offset:1024
	ds_read_b128 v[178:181], v153 offset:2048
	ds_read_b128 v[182:185], v153 offset:3072
	ds_read_b128 v[186:189], v151 offset:32768
	ds_read_b128 v[190:193], v151 offset:33792
	ds_read_b128 v[194:197], v151 offset:34816
	ds_read_b128 v[198:201], v151 offset:35840
	ds_read_b128 v[202:205], v151 offset:36864
	ds_read_b128 v[206:209], v151 offset:37888
	ds_read_b128 v[210:213], v151 offset:38912
	ds_read_b128 v[214:217], v151 offset:39936
	s_waitcnt vmcnt(8)
	s_waitcnt lgkmcnt(0)
	s_setprio 1
	s_barrier
	v_mfma_f32_16x16x32_bf16 v[116:119], v[154:157], v[186:189], v[116:119]
	v_mfma_f32_16x16x32_bf16 v[112:115], v[162:165], v[186:189], v[112:115]
	v_mfma_f32_16x16x32_bf16 v[108:111], v[154:157], v[194:197], v[108:111]
	v_mfma_f32_16x16x32_bf16 v[100:103], v[162:165], v[194:197], v[100:103]
	v_mfma_f32_16x16x32_bf16 v[92:95], v[154:157], v[202:205], v[92:95]
	v_mfma_f32_16x16x32_bf16 v[84:87], v[162:165], v[202:205], v[84:87]
	v_mfma_f32_16x16x32_bf16 v[76:79], v[154:157], v[210:213], v[76:79]
	v_mfma_f32_16x16x32_bf16 v[68:71], v[162:165], v[210:213], v[68:71]
	v_mfma_f32_16x16x32_bf16 v[116:119], v[158:161], v[190:193], v[116:119]
	v_mfma_f32_16x16x32_bf16 v[112:115], v[166:169], v[190:193], v[112:115]
	v_mfma_f32_16x16x32_bf16 v[108:111], v[158:161], v[198:201], v[108:111]
	v_mfma_f32_16x16x32_bf16 v[100:103], v[166:169], v[198:201], v[100:103]
	v_mfma_f32_16x16x32_bf16 v[92:95], v[158:161], v[206:209], v[92:95]
	v_mfma_f32_16x16x32_bf16 v[84:87], v[166:169], v[206:209], v[84:87]
	v_mfma_f32_16x16x32_bf16 v[76:79], v[158:161], v[214:217], v[76:79]
	v_mfma_f32_16x16x32_bf16 v[68:71], v[166:169], v[214:217], v[68:71]
	s_setprio 0
	s_setprio 1
	v_mfma_f32_16x16x32_bf16 v[124:127], v[170:173], v[186:189], v[124:127]
	v_mfma_f32_16x16x32_bf16 v[120:123], v[178:181], v[186:189], v[120:123]
	v_mfma_f32_16x16x32_bf16 v[104:107], v[170:173], v[194:197], v[104:107]
	v_mfma_f32_16x16x32_bf16 v[96:99], v[178:181], v[194:197], v[96:99]
	v_mfma_f32_16x16x32_bf16 v[88:91], v[170:173], v[202:205], v[88:91]
	v_mfma_f32_16x16x32_bf16 v[80:83], v[178:181], v[202:205], v[80:83]
	v_mfma_f32_16x16x32_bf16 v[72:75], v[170:173], v[210:213], v[72:75]
	v_mfma_f32_16x16x32_bf16 v[64:67], v[178:181], v[210:213], v[64:67]
	v_mfma_f32_16x16x32_bf16 v[124:127], v[174:177], v[190:193], v[124:127]
	v_mfma_f32_16x16x32_bf16 v[120:123], v[182:185], v[190:193], v[120:123]
	v_mfma_f32_16x16x32_bf16 v[104:107], v[174:177], v[198:201], v[104:107]
	v_mfma_f32_16x16x32_bf16 v[96:99], v[182:185], v[198:201], v[96:99]
	v_mfma_f32_16x16x32_bf16 v[88:91], v[174:177], v[206:209], v[88:91]
	v_mfma_f32_16x16x32_bf16 v[80:83], v[182:185], v[206:209], v[80:83]
	v_mfma_f32_16x16x32_bf16 v[72:75], v[174:177], v[214:217], v[72:75]
	v_mfma_f32_16x16x32_bf16 v[64:67], v[182:185], v[214:217], v[64:67]
	s_barrier
	s_setprio 0
	s_add_i32 s34, s63, s5
	v_lshl_add_u64 v[144:145], v[144:145], 0, s[12:13]
	s_mov_b32 m0, s34
	s_nop 0
	global_load_lds_dwordx4 v[144:145], off
	s_add_i32 m0, s34, 0x2000
	s_add_u32 s30, s30, 0x40080
	v_lshl_add_u64 v[144:145], v[218:219], 0, s[12:13]
	s_addc_u32 s31, s31, 0
	s_add_i32 s34, s64, s5
	global_load_lds_dwordx4 v[144:145], off
	v_lshl_add_u64 v[144:145], s[30:31], 0, v[132:133]
	s_mov_b32 m0, s34
	s_nop 0
	global_load_lds_dwordx4 v[144:145], off
	v_lshl_add_u64 v[144:145], s[30:31], 0, v[128:129]
	s_add_i32 m0, s34, 0x2000
	s_nop 0
	global_load_lds_dwordx4 v[144:145], off
	v_lshl_add_u64 v[144:145], v[220:221], 0, s[12:13]
	s_mov_b32 m0, s41
	s_nop 0
	global_load_lds_dwordx4 v[144:145], off
	v_lshl_add_u64 v[144:145], v[222:223], 0, s[12:13]
	s_mov_b32 m0, s42
	s_nop 0
	global_load_lds_dwordx4 v[144:145], off
	ds_read_b128 v[186:189], v151 offset:49152
	ds_read_b128 v[190:193], v151 offset:50176
	ds_read_b128 v[194:197], v151 offset:51200
	ds_read_b128 v[198:201], v151 offset:52224
	ds_read_b128 v[202:205], v151 offset:53248
	ds_read_b128 v[206:209], v151 offset:54272
	ds_read_b128 v[210:213], v151 offset:55296
	ds_read_b128 v[214:217], v151 offset:56320
	s_waitcnt vmcnt(8)
	s_waitcnt lgkmcnt(0)
	s_setprio 1
	s_barrier
	v_mfma_f32_16x16x32_bf16 v[60:63], v[154:157], v[186:189], v[60:63]
	v_mfma_f32_16x16x32_bf16 v[52:55], v[162:165], v[186:189], v[52:55]
	v_mfma_f32_16x16x32_bf16 v[44:47], v[154:157], v[194:197], v[44:47]
	v_mfma_f32_16x16x32_bf16 v[36:39], v[162:165], v[194:197], v[36:39]
	v_mfma_f32_16x16x32_bf16 v[28:31], v[154:157], v[202:205], v[28:31]
	v_mfma_f32_16x16x32_bf16 v[20:23], v[162:165], v[202:205], v[20:23]
	v_mfma_f32_16x16x32_bf16 v[12:15], v[154:157], v[210:213], v[12:15]
	v_mfma_f32_16x16x32_bf16 v[4:7], v[162:165], v[210:213], v[4:7]
	v_mfma_f32_16x16x32_bf16 v[60:63], v[158:161], v[190:193], v[60:63]
	v_mfma_f32_16x16x32_bf16 v[52:55], v[166:169], v[190:193], v[52:55]
	v_mfma_f32_16x16x32_bf16 v[44:47], v[158:161], v[198:201], v[44:47]
	v_mfma_f32_16x16x32_bf16 v[36:39], v[166:169], v[198:201], v[36:39]
	v_mfma_f32_16x16x32_bf16 v[28:31], v[158:161], v[206:209], v[28:31]
	v_mfma_f32_16x16x32_bf16 v[20:23], v[166:169], v[206:209], v[20:23]
	v_mfma_f32_16x16x32_bf16 v[12:15], v[158:161], v[214:217], v[12:15]
	v_mfma_f32_16x16x32_bf16 v[4:7], v[166:169], v[214:217], v[4:7]
	s_setprio 0
	s_setprio 1
	v_mfma_f32_16x16x32_bf16 v[56:59], v[170:173], v[186:189], v[56:59]
	v_mfma_f32_16x16x32_bf16 v[48:51], v[178:181], v[186:189], v[48:51]
	v_mfma_f32_16x16x32_bf16 v[40:43], v[170:173], v[194:197], v[40:43]
	v_mfma_f32_16x16x32_bf16 v[32:35], v[178:181], v[194:197], v[32:35]
	v_mfma_f32_16x16x32_bf16 v[24:27], v[170:173], v[202:205], v[24:27]
	v_mfma_f32_16x16x32_bf16 v[16:19], v[178:181], v[202:205], v[16:19]
	v_mfma_f32_16x16x32_bf16 v[8:11], v[170:173], v[210:213], v[8:11]
	v_mfma_f32_16x16x32_bf16 v[0:3], v[178:181], v[210:213], v[0:3]
	v_mfma_f32_16x16x32_bf16 v[56:59], v[174:177], v[190:193], v[56:59]
	v_mfma_f32_16x16x32_bf16 v[48:51], v[182:185], v[190:193], v[48:51]
	v_mfma_f32_16x16x32_bf16 v[40:43], v[174:177], v[198:201], v[40:43]
	v_mfma_f32_16x16x32_bf16 v[32:35], v[182:185], v[198:201], v[32:35]
	v_mfma_f32_16x16x32_bf16 v[24:27], v[174:177], v[206:209], v[24:27]
	v_mfma_f32_16x16x32_bf16 v[16:19], v[182:185], v[206:209], v[16:19]
	v_mfma_f32_16x16x32_bf16 v[8:11], v[174:177], v[214:217], v[8:11]
	v_mfma_f32_16x16x32_bf16 v[0:3], v[182:185], v[214:217], v[0:3]
	s_barrier
	s_setprio 0
	s_add_i32 s62, s62, 2
	s_add_u32 s28, s28, 0x100
	s_addc_u32 s29, s29, 0
	s_add_u32 s60, s60, 0x100
	s_addc_u32 s61, s61, 0
	s_cmp_gt_u32 s62, 13
	s_cbranch_scc0 .LBB0_1193
	s_and_b64 vcc, exec, s[14:15]
	s_cbranch_vccz .LBB0_1196
	s_barrier

.LBB0_1273:
	s_add_u32 s18, s16, 0x100
	s_addc_u32 s19, s17, 0
	s_cmp_eq_u32 s46, 40
	s_cselect_b32 s23, s5, s19
	s_cselect_b32 s22, s4, s18
	s_cselect_b32 s21, s15, s45
	s_cselect_b32 s20, s14, s44
	v_lshl_add_u64 v[192:193], s[16:17], 0, v[172:173]
	s_add_i32 m0, s26, 0xc000
	s_nop 0
	global_load_lds_dwordx4 v[192:193], off
	v_lshl_add_u64 v[192:193], s[16:17], 0, v[174:175]
	s_add_i32 m0, s26, 0xe000
	s_nop 0
	global_load_lds_dwordx4 v[192:193], off
	ds_read_b128 v[128:131], v197
	ds_read_b128 v[132:135], v197 offset:1024
	ds_read_b128 v[136:139], v197 offset:2048
	ds_read_b128 v[140:143], v197 offset:3072
	ds_read_b128 v[144:147], v198
	ds_read_b128 v[148:151], v198 offset:1024
	ds_read_b128 v[152:155], v198 offset:2048
	ds_read_b128 v[156:159], v198 offset:3072
	ds_read_b128 v[160:163], v199
	ds_read_b128 v[180:183], v199 offset:1024
	ds_read_b128 v[184:187], v199 offset:2048
	ds_read_b128 v[188:191], v199 offset:3072
	ds_read_b128 v[200:203], v199 offset:4096
	ds_read_b128 v[204:207], v199 offset:5120
	ds_read_b128 v[208:211], v199 offset:6144
	ds_read_b128 v[212:215], v199 offset:7168
	s_nop 0
	s_waitcnt vmcnt(8)
	s_waitcnt lgkmcnt(0)
	s_setprio 1
	s_barrier
	v_mfma_f32_16x16x32_bf16 v[124:127], v[128:131], v[160:163], v[124:127]
	v_mfma_f32_16x16x32_bf16 v[120:123], v[136:139], v[160:163], v[120:123]
	v_mfma_f32_16x16x32_bf16 v[112:115], v[128:131], v[184:187], v[112:115]
	v_mfma_f32_16x16x32_bf16 v[104:107], v[136:139], v[184:187], v[104:107]
	v_mfma_f32_16x16x32_bf16 v[96:99], v[128:131], v[200:203], v[96:99]
	v_mfma_f32_16x16x32_bf16 v[88:91], v[136:139], v[200:203], v[88:91]
	v_mfma_f32_16x16x32_bf16 v[80:83], v[128:131], v[208:211], v[80:83]
	v_mfma_f32_16x16x32_bf16 v[72:75], v[136:139], v[208:211], v[72:75]
	v_mfma_f32_16x16x32_bf16 v[124:127], v[132:135], v[180:183], v[124:127]
	v_mfma_f32_16x16x32_bf16 v[120:123], v[140:143], v[180:183], v[120:123]
	v_mfma_f32_16x16x32_bf16 v[112:115], v[132:135], v[188:191], v[112:115]
	v_mfma_f32_16x16x32_bf16 v[104:107], v[140:143], v[188:191], v[104:107]
	v_mfma_f32_16x16x32_bf16 v[96:99], v[132:135], v[204:207], v[96:99]
	v_mfma_f32_16x16x32_bf16 v[88:91], v[140:143], v[204:207], v[88:91]
	v_mfma_f32_16x16x32_bf16 v[80:83], v[132:135], v[212:215], v[80:83]
	v_mfma_f32_16x16x32_bf16 v[72:75], v[140:143], v[212:215], v[72:75]
	s_setprio 0
	s_setprio 1
	v_mfma_f32_16x16x32_bf16 v[116:119], v[144:147], v[160:163], v[116:119]
	v_mfma_f32_16x16x32_bf16 v[108:111], v[152:155], v[160:163], v[108:111]
	v_mfma_f32_16x16x32_bf16 v[100:103], v[144:147], v[184:187], v[100:103]
	v_mfma_f32_16x16x32_bf16 v[92:95], v[152:155], v[184:187], v[92:95]
	v_mfma_f32_16x16x32_bf16 v[84:87], v[144:147], v[200:203], v[84:87]
	v_mfma_f32_16x16x32_bf16 v[76:79], v[152:155], v[200:203], v[76:79]
	v_mfma_f32_16x16x32_bf16 v[68:71], v[144:147], v[208:211], v[68:71]
	v_mfma_f32_16x16x32_bf16 v[64:67], v[152:155], v[208:211], v[64:67]
	v_mfma_f32_16x16x32_bf16 v[116:119], v[148:151], v[180:183], v[116:119]
	v_mfma_f32_16x16x32_bf16 v[108:111], v[156:159], v[180:183], v[108:111]
	v_mfma_f32_16x16x32_bf16 v[100:103], v[148:151], v[188:191], v[100:103]
	v_mfma_f32_16x16x32_bf16 v[92:95], v[156:159], v[188:191], v[92:95]
	v_mfma_f32_16x16x32_bf16 v[84:87], v[148:151], v[204:207], v[84:87]
	v_mfma_f32_16x16x32_bf16 v[76:79], v[156:159], v[204:207], v[76:79]
	v_mfma_f32_16x16x32_bf16 v[68:71], v[148:151], v[212:215], v[68:71]
	v_mfma_f32_16x16x32_bf16 v[64:67], v[156:159], v[212:215], v[64:67]
	s_barrier
	s_setprio 0
	s_add_i32 s16, s38, s25
	v_lshl_add_u64 v[192:193], s[20:21], 0, v[166:167]
	s_mov_b32 m0, s16
	s_nop 0
	global_load_lds_dwordx4 v[192:193], off
	s_add_i32 m0, s16, 0x2000
	s_add_u32 s16, s20, 0xb0000
	v_lshl_add_u64 v[216:217], s[20:21], 0, v[170:171]
	s_addc_u32 s17, s21, 0
	s_add_i32 s47, s39, s25
	global_load_lds_dwordx4 v[216:217], off
	v_lshl_add_u64 v[218:219], s[16:17], 0, v[166:167]
	s_mov_b32 m0, s47
	v_lshl_add_u64 v[220:221], s[22:23], 0, v[168:169]
	global_load_lds_dwordx4 v[218:219], off
	v_lshl_add_u64 v[218:219], s[16:17], 0, v[170:171]
	s_add_i32 m0, s47, 0x2000
	s_nop 0
	global_load_lds_dwordx4 v[218:219], off
	v_lshl_add_u64 v[218:219], s[22:23], 0, v[164:165]
	s_mov_b32 m0, s26
	s_nop 0
	global_load_lds_dwordx4 v[218:219], off
	s_mov_b32 m0, s27
	s_nop 0
	global_load_lds_dwordx4 v[220:221], off
	ds_read_b128 v[160:163], v199 offset:16384
	ds_read_b128 v[180:183], v199 offset:17408
	ds_read_b128 v[184:187], v199 offset:18432
	ds_read_b128 v[188:191], v199 offset:19456
	ds_read_b128 v[200:203], v199 offset:20480
	ds_read_b128 v[204:207], v199 offset:21504
	ds_read_b128 v[208:211], v199 offset:22528
	ds_read_b128 v[212:215], v199 offset:23552
	s_nop 0
	s_waitcnt vmcnt(8)
	s_waitcnt lgkmcnt(0)
	s_setprio 1
	s_barrier
	v_mfma_f32_16x16x32_bf16 v[60:63], v[128:131], v[160:163], v[60:63]
	v_mfma_f32_16x16x32_bf16 v[56:59], v[136:139], v[160:163], v[56:59]
	v_mfma_f32_16x16x32_bf16 v[48:51], v[128:131], v[184:187], v[48:51]
	v_mfma_f32_16x16x32_bf16 v[40:43], v[136:139], v[184:187], v[40:43]
	v_mfma_f32_16x16x32_bf16 v[32:35], v[128:131], v[200:203], v[32:35]
	v_mfma_f32_16x16x32_bf16 v[24:27], v[136:139], v[200:203], v[24:27]
	v_mfma_f32_16x16x32_bf16 v[16:19], v[128:131], v[208:211], v[16:19]
	v_mfma_f32_16x16x32_bf16 v[8:11], v[136:139], v[208:211], v[8:11]
	v_mfma_f32_16x16x32_bf16 v[60:63], v[132:135], v[180:183], v[60:63]
	v_mfma_f32_16x16x32_bf16 v[56:59], v[140:143], v[180:183], v[56:59]
	v_mfma_f32_16x16x32_bf16 v[48:51], v[132:135], v[188:191], v[48:51]
	v_mfma_f32_16x16x32_bf16 v[40:43], v[140:143], v[188:191], v[40:43]
	v_mfma_f32_16x16x32_bf16 v[32:35], v[132:135], v[204:207], v[32:35]
	v_mfma_f32_16x16x32_bf16 v[24:27], v[140:143], v[204:207], v[24:27]
	v_mfma_f32_16x16x32_bf16 v[16:19], v[132:135], v[212:215], v[16:19]
	v_mfma_f32_16x16x32_bf16 v[8:11], v[140:143], v[212:215], v[8:11]
	s_setprio 0
	s_setprio 1
	v_mfma_f32_16x16x32_bf16 v[52:55], v[144:147], v[160:163], v[52:55]
	v_mfma_f32_16x16x32_bf16 v[44:47], v[152:155], v[160:163], v[44:47]
	v_mfma_f32_16x16x32_bf16 v[36:39], v[144:147], v[184:187], v[36:39]
	v_mfma_f32_16x16x32_bf16 v[28:31], v[152:155], v[184:187], v[28:31]
	v_mfma_f32_16x16x32_bf16 v[20:23], v[144:147], v[200:203], v[20:23]
	v_mfma_f32_16x16x32_bf16 v[12:15], v[152:155], v[200:203], v[12:15]
	v_mfma_f32_16x16x32_bf16 v[4:7], v[144:147], v[208:211], v[4:7]
	v_mfma_f32_16x16x32_bf16 v[0:3], v[152:155], v[208:211], v[0:3]
	v_mfma_f32_16x16x32_bf16 v[52:55], v[148:151], v[180:183], v[52:55]
	v_mfma_f32_16x16x32_bf16 v[44:47], v[156:159], v[180:183], v[44:47]
	v_mfma_f32_16x16x32_bf16 v[36:39], v[148:151], v[188:191], v[36:39]
	v_mfma_f32_16x16x32_bf16 v[28:31], v[156:159], v[188:191], v[28:31]
	v_mfma_f32_16x16x32_bf16 v[20:23], v[148:151], v[204:207], v[20:23]
	v_mfma_f32_16x16x32_bf16 v[12:15], v[156:159], v[204:207], v[12:15]
	v_mfma_f32_16x16x32_bf16 v[4:7], v[148:151], v[212:215], v[4:7]
	v_mfma_f32_16x16x32_bf16 v[0:3], v[156:159], v[212:215], v[0:3]
	s_barrier
	s_setprio 0
	s_add_i32 s47, 0, 0x18000
	s_add_i32 s48, 0, 0x1c000
	s_add_u32 s16, s22, 0xb0000
	s_addc_u32 s17, s23, 0
	s_mov_b32 m0, s28
	v_lshl_add_u64 v[222:223], s[16:17], 0, v[164:165]
	global_load_lds_dwordx4 v[222:223], off
	v_lshl_add_u64 v[222:223], s[16:17], 0, v[168:169]
	s_mov_b32 m0, s29
	s_nop 0
	global_load_lds_dwordx4 v[222:223], off
	v_add_u32_e32 v140, s47, v196
	v_add_u32_e32 v156, s48, v196
	ds_read_b128 v[128:131], v140
	ds_read_b128 v[132:135], v140 offset:1024
	ds_read_b128 v[136:139], v140 offset:2048
	ds_read_b128 v[140:143], v140 offset:3072
	ds_read_b128 v[144:147], v156
	ds_read_b128 v[148:151], v156 offset:1024
	ds_read_b128 v[152:155], v156 offset:2048
	ds_read_b128 v[156:159], v156 offset:3072
	ds_read_b128 v[160:163], v199 offset:32768
	ds_read_b128 v[180:183], v199 offset:33792
	ds_read_b128 v[184:187], v199 offset:34816
	ds_read_b128 v[188:191], v199 offset:35840
	ds_read_b128 v[200:203], v199 offset:36864
	ds_read_b128 v[204:207], v199 offset:37888
	ds_read_b128 v[208:211], v199 offset:38912
	ds_read_b128 v[212:215], v199 offset:39936
	s_waitcnt vmcnt(8)
	s_waitcnt lgkmcnt(0)
	s_setprio 1
	s_barrier
	v_mfma_f32_16x16x32_bf16 v[124:127], v[128:131], v[160:163], v[124:127]
	v_mfma_f32_16x16x32_bf16 v[120:123], v[136:139], v[160:163], v[120:123]
	v_mfma_f32_16x16x32_bf16 v[112:115], v[128:131], v[184:187], v[112:115]
	v_mfma_f32_16x16x32_bf16 v[104:107], v[136:139], v[184:187], v[104:107]
	v_mfma_f32_16x16x32_bf16 v[96:99], v[128:131], v[200:203], v[96:99]
	v_mfma_f32_16x16x32_bf16 v[88:91], v[136:139], v[200:203], v[88:91]
	v_mfma_f32_16x16x32_bf16 v[80:83], v[128:131], v[208:211], v[80:83]
	v_mfma_f32_16x16x32_bf16 v[72:75], v[136:139], v[208:211], v[72:75]
	v_mfma_f32_16x16x32_bf16 v[124:127], v[132:135], v[180:183], v[124:127]
	v_mfma_f32_16x16x32_bf16 v[120:123], v[140:143], v[180:183], v[120:123]
	v_mfma_f32_16x16x32_bf16 v[112:115], v[132:135], v[188:191], v[112:115]
	v_mfma_f32_16x16x32_bf16 v[104:107], v[140:143], v[188:191], v[104:107]
	v_mfma_f32_16x16x32_bf16 v[96:99], v[132:135], v[204:207], v[96:99]
	v_mfma_f32_16x16x32_bf16 v[88:91], v[140:143], v[204:207], v[88:91]
	v_mfma_f32_16x16x32_bf16 v[80:83], v[132:135], v[212:215], v[80:83]
	v_mfma_f32_16x16x32_bf16 v[72:75], v[140:143], v[212:215], v[72:75]
	s_setprio 0
	s_setprio 1
	v_mfma_f32_16x16x32_bf16 v[116:119], v[144:147], v[160:163], v[116:119]
	v_mfma_f32_16x16x32_bf16 v[108:111], v[152:155], v[160:163], v[108:111]
	v_mfma_f32_16x16x32_bf16 v[100:103], v[144:147], v[184:187], v[100:103]
	v_mfma_f32_16x16x32_bf16 v[92:95], v[152:155], v[184:187], v[92:95]
	v_mfma_f32_16x16x32_bf16 v[84:87], v[144:147], v[200:203], v[84:87]
	v_mfma_f32_16x16x32_bf16 v[76:79], v[152:155], v[200:203], v[76:79]
	v_mfma_f32_16x16x32_bf16 v[68:71], v[144:147], v[208:211], v[68:71]
	v_mfma_f32_16x16x32_bf16 v[64:67], v[152:155], v[208:211], v[64:67]
	v_mfma_f32_16x16x32_bf16 v[116:119], v[148:151], v[180:183], v[116:119]
	v_mfma_f32_16x16x32_bf16 v[108:111], v[156:159], v[180:183], v[108:111]
	v_mfma_f32_16x16x32_bf16 v[100:103], v[148:151], v[188:191], v[100:103]
	v_mfma_f32_16x16x32_bf16 v[92:95], v[156:159], v[188:191], v[92:95]
	v_mfma_f32_16x16x32_bf16 v[84:87], v[148:151], v[204:207], v[84:87]
	v_mfma_f32_16x16x32_bf16 v[76:79], v[156:159], v[204:207], v[76:79]
	v_mfma_f32_16x16x32_bf16 v[68:71], v[148:151], v[212:215], v[68:71]
	v_mfma_f32_16x16x32_bf16 v[64:67], v[156:159], v[212:215], v[64:67]
	s_barrier
	s_setprio 0
	s_add_i32 s16, s47, s25
	v_lshl_add_u64 v[192:193], v[192:193], 0, s[10:11]
	s_mov_b32 m0, s16
	s_nop 0
	global_load_lds_dwordx4 v[192:193], off
	s_add_i32 m0, s16, 0x2000
	s_add_u32 s16, s20, 0xb0080
	v_lshl_add_u64 v[192:193], v[216:217], 0, s[10:11]
	s_addc_u32 s17, s21, 0
	s_add_i32 s20, s48, s25
	global_load_lds_dwordx4 v[192:193], off
	v_lshl_add_u64 v[192:193], s[16:17], 0, v[166:167]
	s_mov_b32 m0, s20
	s_nop 0
	global_load_lds_dwordx4 v[192:193], off
	v_lshl_add_u64 v[192:193], s[16:17], 0, v[170:171]
	s_add_i32 m0, s20, 0x2000
	s_nop 0
	global_load_lds_dwordx4 v[192:193], off
	v_lshl_add_u64 v[192:193], v[218:219], 0, s[10:11]
	s_mov_b32 m0, s35
	s_nop 0
	global_load_lds_dwordx4 v[192:193], off
	v_lshl_add_u64 v[192:193], v[220:221], 0, s[10:11]
	s_mov_b32 m0, s36
	s_nop 0
	global_load_lds_dwordx4 v[192:193], off
	ds_read_b128 v[160:163], v199 offset:49152
	ds_read_b128 v[180:183], v199 offset:50176
	ds_read_b128 v[184:187], v199 offset:51200
	ds_read_b128 v[188:191], v199 offset:52224
	ds_read_b128 v[200:203], v199 offset:53248
	ds_read_b128 v[204:207], v199 offset:54272
	ds_read_b128 v[208:211], v199 offset:55296
	ds_read_b128 v[212:215], v199 offset:56320
	s_waitcnt vmcnt(8)
	s_waitcnt lgkmcnt(0)
	s_setprio 1
	s_barrier
	v_mfma_f32_16x16x32_bf16 v[60:63], v[128:131], v[160:163], v[60:63]
	v_mfma_f32_16x16x32_bf16 v[56:59], v[136:139], v[160:163], v[56:59]
	v_mfma_f32_16x16x32_bf16 v[48:51], v[128:131], v[184:187], v[48:51]
	v_mfma_f32_16x16x32_bf16 v[40:43], v[136:139], v[184:187], v[40:43]
	v_mfma_f32_16x16x32_bf16 v[32:35], v[128:131], v[200:203], v[32:35]
	v_mfma_f32_16x16x32_bf16 v[24:27], v[136:139], v[200:203], v[24:27]
	v_mfma_f32_16x16x32_bf16 v[16:19], v[128:131], v[208:211], v[16:19]
	v_mfma_f32_16x16x32_bf16 v[8:11], v[136:139], v[208:211], v[8:11]
	v_mfma_f32_16x16x32_bf16 v[60:63], v[132:135], v[180:183], v[60:63]
	v_mfma_f32_16x16x32_bf16 v[56:59], v[140:143], v[180:183], v[56:59]
	v_mfma_f32_16x16x32_bf16 v[48:51], v[132:135], v[188:191], v[48:51]
	v_mfma_f32_16x16x32_bf16 v[40:43], v[140:143], v[188:191], v[40:43]
	v_mfma_f32_16x16x32_bf16 v[32:35], v[132:135], v[204:207], v[32:35]
	v_mfma_f32_16x16x32_bf16 v[24:27], v[140:143], v[204:207], v[24:27]
	v_mfma_f32_16x16x32_bf16 v[16:19], v[132:135], v[212:215], v[16:19]
	v_mfma_f32_16x16x32_bf16 v[8:11], v[140:143], v[212:215], v[8:11]
	s_setprio 0
	s_setprio 1
	v_mfma_f32_16x16x32_bf16 v[52:55], v[144:147], v[160:163], v[52:55]
	v_mfma_f32_16x16x32_bf16 v[44:47], v[152:155], v[160:163], v[44:47]
	v_mfma_f32_16x16x32_bf16 v[36:39], v[144:147], v[184:187], v[36:39]
	v_mfma_f32_16x16x32_bf16 v[28:31], v[152:155], v[184:187], v[28:31]
	v_mfma_f32_16x16x32_bf16 v[20:23], v[144:147], v[200:203], v[20:23]
	v_mfma_f32_16x16x32_bf16 v[12:15], v[152:155], v[200:203], v[12:15]
	v_mfma_f32_16x16x32_bf16 v[4:7], v[144:147], v[208:211], v[4:7]
	v_mfma_f32_16x16x32_bf16 v[0:3], v[152:155], v[208:211], v[0:3]
	v_mfma_f32_16x16x32_bf16 v[52:55], v[148:151], v[180:183], v[52:55]
	v_mfma_f32_16x16x32_bf16 v[44:47], v[156:159], v[180:183], v[44:47]
	v_mfma_f32_16x16x32_bf16 v[36:39], v[148:151], v[188:191], v[36:39]
	v_mfma_f32_16x16x32_bf16 v[28:31], v[156:159], v[188:191], v[28:31]
	v_mfma_f32_16x16x32_bf16 v[20:23], v[148:151], v[204:207], v[20:23]
	v_mfma_f32_16x16x32_bf16 v[12:15], v[156:159], v[204:207], v[12:15]
	v_mfma_f32_16x16x32_bf16 v[4:7], v[148:151], v[212:215], v[4:7]
	v_mfma_f32_16x16x32_bf16 v[0:3], v[156:159], v[212:215], v[0:3]
	s_barrier
	s_setprio 0
	s_add_i32 s46, s46, 2
	s_add_u32 s44, s44, 0x100
	s_addc_u32 s45, s45, 0
	s_cmp_gt_u32 s46, 41
	s_mov_b64 s[16:17], s[18:19]
	s_cbranch_scc0 .LBB0_1273
	s_and_b64 vcc, exec, s[12:13]
	s_cbranch_vccz .LBB0_1276
	s_barrier
